# fwd substitution: per-column-block code skipping all-zero quads, single accumulator, packed subtract
# speedup vs baseline: 1.0550x; 1.0011x over previous
; #define LAS __attribute__((address_space(3)))
;     ...
; #pragma unroll
;         for (int ip = 0; ip < 32; ++ip) {
;             const int i0 = 2 * ip;
;             f32x4 rv[32];
; #pragma unroll
;             for (int jp = 0; jp <= ip; ++jp) rv[jp] = *(const LAS f32x4*)(Ad + ip * 136 + 4 * jp);
;             asm volatile("" : "+v"(lane_o) :: "memory");
;             f32x2_ a0 = {0.f, 0.f}, a1 = {0.f, 0.f}, a2 = {0.f, 0.f}, a3 = {0.f, 0.f};
; #pragma unroll
;             for (int jp = 0; jp < ip; ++jp) {
;                 const f32x2_ ta = {tr[2 * jp], tr[2 * jp]}, tb = {tr[2 * jp + 1], tr[2 * jp + 1]};
;                 const f32x2_ va = {rv[jp][0], rv[jp][1]}, vb = {rv[jp][2], rv[jp][3]};
;                 if (jp & 1) { a2 += va * ta; a3 += vb * tb; } else { a0 += va * ta; a1 += vb * tb; }
;             }
;             const f32x2_ sum = (a0 + a1) + (a2 + a3);
;             const float t0 = (lane_o == i0 ? 1.f : 0.f) - sum[0];
;             tr[i0] = t0;
;             tr[i0 + 1] = (lane_o == i0 + 1 ? 1.f : 0.f) - sum[1] - rv[ip][1] * t0;
;         }
.Lfs_ent0:
	ds_read_b128 v[70:73], v14 offset:0
	ds_read_b128 v[122:125], v14 offset:544
	s_waitcnt lgkmcnt(1)
	v_pk_fma_f32 v[62:63], v[70:71], v[2:3], 0 op_sel_hi:[1,0,0]
	v_pk_fma_f32 v[62:63], v[72:73], v[2:3], v[62:63] op_sel:[0,1,0] op_sel_hi:[1,1,1]
	s_nop 1
	v_add_f32_dpp v62, v62, v62 quad_perm:[1,0,3,2] row_mask:0xf bank_mask:0xf bound_ctrl:1
	v_add_f32_dpp v63, v63, v63 quad_perm:[1,0,3,2] row_mask:0xf bank_mask:0xf bound_ctrl:1
	s_nop 0
	v_add_f32_dpp v62, v62, v62 quad_perm:[2,3,0,1] row_mask:0xf bank_mask:0xf bound_ctrl:1
	v_add_f32_dpp v63, v63, v63 quad_perm:[2,3,0,1] row_mask:0xf bank_mask:0xf bound_ctrl:1
	s_mov_b64 exec, s[4:5]
	v_pk_add_f32 v[2:3], v[2:3], v[62:63] neg_lo:[0,1] neg_hi:[0,1]
	v_fma_f32 v3, v71, v62, v3
	s_mov_b64 exec, -1
	ds_read_b128 v[70:73], v14 offset:1088
	s_waitcnt lgkmcnt(1)
	v_pk_fma_f32 v[62:63], v[122:123], v[2:3], 0 op_sel_hi:[1,0,0]
	v_pk_fma_f32 v[62:63], v[124:125], v[2:3], v[62:63] op_sel:[0,1,0] op_sel_hi:[1,1,1]
	s_nop 1
	v_add_f32_dpp v62, v62, v62 quad_perm:[1,0,3,2] row_mask:0xf bank_mask:0xf bound_ctrl:1
	v_add_f32_dpp v63, v63, v63 quad_perm:[1,0,3,2] row_mask:0xf bank_mask:0xf bound_ctrl:1
	s_nop 0
	v_add_f32_dpp v62, v62, v62 quad_perm:[2,3,0,1] row_mask:0xf bank_mask:0xf bound_ctrl:1
	v_add_f32_dpp v63, v63, v63 quad_perm:[2,3,0,1] row_mask:0xf bank_mask:0xf bound_ctrl:1
	s_mov_b64 exec, s[6:7]
	v_pk_add_f32 v[2:3], v[2:3], v[62:63] neg_lo:[0,1] neg_hi:[0,1]
	v_fma_f32 v3, v123, v62, v3
	s_mov_b64 exec, -1
	ds_read_b128 v[122:125], v14 offset:1632
	s_waitcnt lgkmcnt(1)
	v_pk_fma_f32 v[62:63], v[70:71], v[2:3], 0 op_sel_hi:[1,0,0]
	v_pk_fma_f32 v[62:63], v[72:73], v[2:3], v[62:63] op_sel:[0,1,0] op_sel_hi:[1,1,1]
	s_nop 1
	v_add_f32_dpp v62, v62, v62 quad_perm:[1,0,3,2] row_mask:0xf bank_mask:0xf bound_ctrl:1
	v_add_f32_dpp v63, v63, v63 quad_perm:[1,0,3,2] row_mask:0xf bank_mask:0xf bound_ctrl:1
	s_nop 0
	v_add_f32_dpp v62, v62, v62 quad_perm:[2,3,0,1] row_mask:0xf bank_mask:0xf bound_ctrl:1
	v_add_f32_dpp v63, v63, v63 quad_perm:[2,3,0,1] row_mask:0xf bank_mask:0xf bound_ctrl:1
	s_mov_b64 exec, s[8:9]
	v_pk_add_f32 v[2:3], v[2:3], v[62:63] neg_lo:[0,1] neg_hi:[0,1]
	v_fma_f32 v3, v71, v62, v3
	s_mov_b64 exec, -1
	ds_read_b128 v[70:73], v14 offset:2176
	ds_read_b128 v[74:77], v14 offset:2240
	s_waitcnt lgkmcnt(2)
	v_pk_fma_f32 v[62:63], v[122:123], v[2:3], 0 op_sel_hi:[1,0,0]
	v_pk_fma_f32 v[62:63], v[124:125], v[2:3], v[62:63] op_sel:[0,1,0] op_sel_hi:[1,1,1]
	s_nop 1
	v_add_f32_dpp v62, v62, v62 quad_perm:[1,0,3,2] row_mask:0xf bank_mask:0xf bound_ctrl:1
	v_add_f32_dpp v63, v63, v63 quad_perm:[1,0,3,2] row_mask:0xf bank_mask:0xf bound_ctrl:1
	s_nop 0
	v_add_f32_dpp v62, v62, v62 quad_perm:[2,3,0,1] row_mask:0xf bank_mask:0xf bound_ctrl:1
	v_add_f32_dpp v63, v63, v63 quad_perm:[2,3,0,1] row_mask:0xf bank_mask:0xf bound_ctrl:1
	s_mov_b64 exec, s[10:11]
	v_pk_add_f32 v[2:3], v[2:3], v[62:63] neg_lo:[0,1] neg_hi:[0,1]
	v_fma_f32 v3, v123, v62, v3
	s_mov_b64 exec, -1
	ds_read_b128 v[122:125], v14 offset:2720
	ds_read_b128 v[126:129], v14 offset:2784
	s_waitcnt lgkmcnt(2)
	v_pk_fma_f32 v[62:63], v[74:75], v[4:5], 0 op_sel_hi:[1,0,0]
	v_pk_fma_f32 v[62:63], v[76:77], v[4:5], v[62:63] op_sel:[0,1,0] op_sel_hi:[1,1,1]
	v_pk_fma_f32 v[62:63], v[70:71], v[2:3], v[62:63] op_sel_hi:[1,0,1]
	v_pk_fma_f32 v[62:63], v[72:73], v[2:3], v[62:63] op_sel:[0,1,0] op_sel_hi:[1,1,1]
	s_nop 1
	v_add_f32_dpp v62, v62, v62 quad_perm:[1,0,3,2] row_mask:0xf bank_mask:0xf bound_ctrl:1
	v_add_f32_dpp v63, v63, v63 quad_perm:[1,0,3,2] row_mask:0xf bank_mask:0xf bound_ctrl:1
	s_nop 0
	v_add_f32_dpp v62, v62, v62 quad_perm:[2,3,0,1] row_mask:0xf bank_mask:0xf bound_ctrl:1
	v_add_f32_dpp v63, v63, v63 quad_perm:[2,3,0,1] row_mask:0xf bank_mask:0xf bound_ctrl:1
	s_mov_b64 exec, s[4:5]
	v_pk_add_f32 v[4:5], v[4:5], v[62:63] neg_lo:[0,1] neg_hi:[0,1]
	v_fma_f32 v5, v75, v62, v5
	s_mov_b64 exec, -1
	ds_read_b128 v[70:73], v14 offset:3264
	ds_read_b128 v[74:77], v14 offset:3328
	s_waitcnt lgkmcnt(2)
	v_pk_fma_f32 v[62:63], v[122:123], v[2:3], 0 op_sel_hi:[1,0,0]
	v_pk_fma_f32 v[62:63], v[124:125], v[2:3], v[62:63] op_sel:[0,1,0] op_sel_hi:[1,1,1]
	v_pk_fma_f32 v[62:63], v[126:127], v[4:5], v[62:63] op_sel_hi:[1,0,1]
	v_pk_fma_f32 v[62:63], v[128:129], v[4:5], v[62:63] op_sel:[0,1,0] op_sel_hi:[1,1,1]
	s_nop 1
	v_add_f32_dpp v62, v62, v62 quad_perm:[1,0,3,2] row_mask:0xf bank_mask:0xf bound_ctrl:1
	v_add_f32_dpp v63, v63, v63 quad_perm:[1,0,3,2] row_mask:0xf bank_mask:0xf bound_ctrl:1
	s_nop 0
	v_add_f32_dpp v62, v62, v62 quad_perm:[2,3,0,1] row_mask:0xf bank_mask:0xf bound_ctrl:1
	v_add_f32_dpp v63, v63, v63 quad_perm:[2,3,0,1] row_mask:0xf bank_mask:0xf bound_ctrl:1
	s_mov_b64 exec, s[6:7]
	v_pk_add_f32 v[4:5], v[4:5], v[62:63] neg_lo:[0,1] neg_hi:[0,1]
	v_fma_f32 v5, v127, v62, v5
	s_mov_b64 exec, -1
	ds_read_b128 v[122:125], v14 offset:3808
	ds_read_b128 v[126:129], v14 offset:3872
	s_waitcnt lgkmcnt(2)
	v_pk_fma_f32 v[62:63], v[70:71], v[2:3], 0 op_sel_hi:[1,0,0]
	v_pk_fma_f32 v[62:63], v[72:73], v[2:3], v[62:63] op_sel:[0,1,0] op_sel_hi:[1,1,1]
	v_pk_fma_f32 v[62:63], v[74:75], v[4:5], v[62:63] op_sel_hi:[1,0,1]
	v_pk_fma_f32 v[62:63], v[76:77], v[4:5], v[62:63] op_sel:[0,1,0] op_sel_hi:[1,1,1]
	s_nop 1
	v_add_f32_dpp v62, v62, v62 quad_perm:[1,0,3,2] row_mask:0xf bank_mask:0xf bound_ctrl:1
	v_add_f32_dpp v63, v63, v63 quad_perm:[1,0,3,2] row_mask:0xf bank_mask:0xf bound_ctrl:1
	s_nop 0
	v_add_f32_dpp v62, v62, v62 quad_perm:[2,3,0,1] row_mask:0xf bank_mask:0xf bound_ctrl:1
	v_add_f32_dpp v63, v63, v63 quad_perm:[2,3,0,1] row_mask:0xf bank_mask:0xf bound_ctrl:1
	s_mov_b64 exec, s[8:9]
	v_pk_add_f32 v[4:5], v[4:5], v[62:63] neg_lo:[0,1] neg_hi:[0,1]
	v_fma_f32 v5, v75, v62, v5
	s_mov_b64 exec, -1
	ds_read_b128 v[70:73], v14 offset:4352
	ds_read_b128 v[74:77], v14 offset:4416
	ds_read_b128 v[78:81], v14 offset:4480
	s_waitcnt lgkmcnt(3)
; #define LAS __attribute__((address_space(3)))
;     ...
; #pragma unroll
;         for (int ip = 0; ip < 32; ++ip) {
;             const int i0 = 2 * ip;
;             f32x4 rv[32];
; #pragma unroll
;             for (int jp = 0; jp <= ip; ++jp) rv[jp] = *(const LAS f32x4*)(Ad + ip * 136 + 4 * jp);
;             asm volatile("" : "+v"(lane_o) :: "memory");
;             f32x2_ a0 = {0.f, 0.f}, a1 = {0.f, 0.f}, a2 = {0.f, 0.f}, a3 = {0.f, 0.f};
; #pragma unroll
;             for (int jp = 0; jp < ip; ++jp) {
;                 const f32x2_ ta = {tr[2 * jp], tr[2 * jp]}, tb = {tr[2 * jp + 1], tr[2 * jp + 1]};
;                 const f32x2_ va = {rv[jp][0], rv[jp][1]}, vb = {rv[jp][2], rv[jp][3]};
;                 if (jp & 1) { a2 += va * ta; a3 += vb * tb; } else { a0 += va * ta; a1 += vb * tb; }
;             }
;             const f32x2_ sum = (a0 + a1) + (a2 + a3);
;             const float t0 = (lane_o == i0 ? 1.f : 0.f) - sum[0];
;             tr[i0] = t0;
;             tr[i0 + 1] = (lane_o == i0 + 1 ? 1.f : 0.f) - sum[1] - rv[ip][1] * t0;
;         }
	v_pk_fma_f32 v[62:63], v[122:123], v[2:3], 0 op_sel_hi:[1,0,0]
	v_pk_fma_f32 v[62:63], v[124:125], v[2:3], v[62:63] op_sel:[0,1,0] op_sel_hi:[1,1,1]
	v_pk_fma_f32 v[62:63], v[126:127], v[4:5], v[62:63] op_sel_hi:[1,0,1]
	v_pk_fma_f32 v[62:63], v[128:129], v[4:5], v[62:63] op_sel:[0,1,0] op_sel_hi:[1,1,1]
	s_nop 1
	v_add_f32_dpp v62, v62, v62 quad_perm:[1,0,3,2] row_mask:0xf bank_mask:0xf bound_ctrl:1
	v_add_f32_dpp v63, v63, v63 quad_perm:[1,0,3,2] row_mask:0xf bank_mask:0xf bound_ctrl:1
	s_nop 0
	v_add_f32_dpp v62, v62, v62 quad_perm:[2,3,0,1] row_mask:0xf bank_mask:0xf bound_ctrl:1
	v_add_f32_dpp v63, v63, v63 quad_perm:[2,3,0,1] row_mask:0xf bank_mask:0xf bound_ctrl:1
	s_mov_b64 exec, s[10:11]
	v_pk_add_f32 v[4:5], v[4:5], v[62:63] neg_lo:[0,1] neg_hi:[0,1]
	v_fma_f32 v5, v127, v62, v5
	s_mov_b64 exec, -1
	ds_read_b128 v[122:125], v14 offset:4896
	ds_read_b128 v[126:129], v14 offset:4960
	ds_read_b128 v[130:133], v14 offset:5024
	s_waitcnt lgkmcnt(3)
	v_pk_fma_f32 v[62:63], v[70:71], v[2:3], 0 op_sel_hi:[1,0,0]
	v_pk_fma_f32 v[62:63], v[72:73], v[2:3], v[62:63] op_sel:[0,1,0] op_sel_hi:[1,1,1]
	v_pk_fma_f32 v[62:63], v[78:79], v[8:9], v[62:63] op_sel_hi:[1,0,1]
	v_pk_fma_f32 v[62:63], v[80:81], v[8:9], v[62:63] op_sel:[0,1,0] op_sel_hi:[1,1,1]
	v_pk_fma_f32 v[62:63], v[74:75], v[4:5], v[62:63] op_sel_hi:[1,0,1]
	v_pk_fma_f32 v[62:63], v[76:77], v[4:5], v[62:63] op_sel:[0,1,0] op_sel_hi:[1,1,1]
	s_nop 1
	v_add_f32_dpp v62, v62, v62 quad_perm:[1,0,3,2] row_mask:0xf bank_mask:0xf bound_ctrl:1
	v_add_f32_dpp v63, v63, v63 quad_perm:[1,0,3,2] row_mask:0xf bank_mask:0xf bound_ctrl:1
	s_nop 0
	v_add_f32_dpp v62, v62, v62 quad_perm:[2,3,0,1] row_mask:0xf bank_mask:0xf bound_ctrl:1
	v_add_f32_dpp v63, v63, v63 quad_perm:[2,3,0,1] row_mask:0xf bank_mask:0xf bound_ctrl:1
	s_mov_b64 exec, s[4:5]
	v_pk_add_f32 v[8:9], v[8:9], v[62:63] neg_lo:[0,1] neg_hi:[0,1]
	v_fma_f32 v9, v79, v62, v9
	s_mov_b64 exec, -1
	ds_read_b128 v[70:73], v14 offset:5440
	ds_read_b128 v[74:77], v14 offset:5504
	ds_read_b128 v[78:81], v14 offset:5568
	s_waitcnt lgkmcnt(3)
	v_pk_fma_f32 v[62:63], v[122:123], v[2:3], 0 op_sel_hi:[1,0,0]
	v_pk_fma_f32 v[62:63], v[124:125], v[2:3], v[62:63] op_sel:[0,1,0] op_sel_hi:[1,1,1]
	v_pk_fma_f32 v[62:63], v[126:127], v[4:5], v[62:63] op_sel_hi:[1,0,1]
	v_pk_fma_f32 v[62:63], v[128:129], v[4:5], v[62:63] op_sel:[0,1,0] op_sel_hi:[1,1,1]
	v_pk_fma_f32 v[62:63], v[130:131], v[8:9], v[62:63] op_sel_hi:[1,0,1]
	v_pk_fma_f32 v[62:63], v[132:133], v[8:9], v[62:63] op_sel:[0,1,0] op_sel_hi:[1,1,1]
	s_nop 1
	v_add_f32_dpp v62, v62, v62 quad_perm:[1,0,3,2] row_mask:0xf bank_mask:0xf bound_ctrl:1
	v_add_f32_dpp v63, v63, v63 quad_perm:[1,0,3,2] row_mask:0xf bank_mask:0xf bound_ctrl:1
	s_nop 0
	v_add_f32_dpp v62, v62, v62 quad_perm:[2,3,0,1] row_mask:0xf bank_mask:0xf bound_ctrl:1
	v_add_f32_dpp v63, v63, v63 quad_perm:[2,3,0,1] row_mask:0xf bank_mask:0xf bound_ctrl:1
	s_mov_b64 exec, s[6:7]
	v_pk_add_f32 v[8:9], v[8:9], v[62:63] neg_lo:[0,1] neg_hi:[0,1]
	v_fma_f32 v9, v131, v62, v9
	s_mov_b64 exec, -1
	ds_read_b128 v[122:125], v14 offset:5984
	ds_read_b128 v[126:129], v14 offset:6048
	ds_read_b128 v[130:133], v14 offset:6112
	s_waitcnt lgkmcnt(3)
	v_pk_fma_f32 v[62:63], v[70:71], v[2:3], 0 op_sel_hi:[1,0,0]
	v_pk_fma_f32 v[62:63], v[72:73], v[2:3], v[62:63] op_sel:[0,1,0] op_sel_hi:[1,1,1]
	v_pk_fma_f32 v[62:63], v[74:75], v[4:5], v[62:63] op_sel_hi:[1,0,1]
	v_pk_fma_f32 v[62:63], v[76:77], v[4:5], v[62:63] op_sel:[0,1,0] op_sel_hi:[1,1,1]
	v_pk_fma_f32 v[62:63], v[78:79], v[8:9], v[62:63] op_sel_hi:[1,0,1]
	v_pk_fma_f32 v[62:63], v[80:81], v[8:9], v[62:63] op_sel:[0,1,0] op_sel_hi:[1,1,1]
	s_nop 1
	v_add_f32_dpp v62, v62, v62 quad_perm:[1,0,3,2] row_mask:0xf bank_mask:0xf bound_ctrl:1
	v_add_f32_dpp v63, v63, v63 quad_perm:[1,0,3,2] row_mask:0xf bank_mask:0xf bound_ctrl:1
	s_nop 0
	v_add_f32_dpp v62, v62, v62 quad_perm:[2,3,0,1] row_mask:0xf bank_mask:0xf bound_ctrl:1
	v_add_f32_dpp v63, v63, v63 quad_perm:[2,3,0,1] row_mask:0xf bank_mask:0xf bound_ctrl:1
	s_mov_b64 exec, s[8:9]
	v_pk_add_f32 v[8:9], v[8:9], v[62:63] neg_lo:[0,1] neg_hi:[0,1]
	v_fma_f32 v9, v79, v62, v9
	s_mov_b64 exec, -1
	ds_read_b128 v[70:73], v14 offset:6528
	ds_read_b128 v[74:77], v14 offset:6592
	ds_read_b128 v[78:81], v14 offset:6656
	ds_read_b128 v[82:85], v14 offset:6720
	s_waitcnt lgkmcnt(4)
	v_pk_fma_f32 v[62:63], v[122:123], v[2:3], 0 op_sel_hi:[1,0,0]
	v_pk_fma_f32 v[62:63], v[124:125], v[2:3], v[62:63] op_sel:[0,1,0] op_sel_hi:[1,1,1]
	v_pk_fma_f32 v[62:63], v[126:127], v[4:5], v[62:63] op_sel_hi:[1,0,1]
	v_pk_fma_f32 v[62:63], v[128:129], v[4:5], v[62:63] op_sel:[0,1,0] op_sel_hi:[1,1,1]
	v_pk_fma_f32 v[62:63], v[130:131], v[8:9], v[62:63] op_sel_hi:[1,0,1]
	v_pk_fma_f32 v[62:63], v[132:133], v[8:9], v[62:63] op_sel:[0,1,0] op_sel_hi:[1,1,1]
	s_nop 1
	v_add_f32_dpp v62, v62, v62 quad_perm:[1,0,3,2] row_mask:0xf bank_mask:0xf bound_ctrl:1
	v_add_f32_dpp v63, v63, v63 quad_perm:[1,0,3,2] row_mask:0xf bank_mask:0xf bound_ctrl:1
	s_nop 0
	v_add_f32_dpp v62, v62, v62 quad_perm:[2,3,0,1] row_mask:0xf bank_mask:0xf bound_ctrl:1
	v_add_f32_dpp v63, v63, v63 quad_perm:[2,3,0,1] row_mask:0xf bank_mask:0xf bound_ctrl:1
	s_mov_b64 exec, s[10:11]
	v_pk_add_f32 v[8:9], v[8:9], v[62:63] neg_lo:[0,1] neg_hi:[0,1]
	v_fma_f32 v9, v131, v62, v9
	s_mov_b64 exec, -1
	ds_read_b128 v[122:125], v14 offset:7072
	ds_read_b128 v[126:129], v14 offset:7136
	ds_read_b128 v[130:133], v14 offset:7200
	ds_read_b128 v[38:41], v14 offset:7264
	s_waitcnt lgkmcnt(4)
; #define LAS __attribute__((address_space(3)))
;     ...
; #pragma unroll
;         for (int ip = 0; ip < 32; ++ip) {
;             const int i0 = 2 * ip;
;             f32x4 rv[32];
; #pragma unroll
;             for (int jp = 0; jp <= ip; ++jp) rv[jp] = *(const LAS f32x4*)(Ad + ip * 136 + 4 * jp);
;             asm volatile("" : "+v"(lane_o) :: "memory");
;             f32x2_ a0 = {0.f, 0.f}, a1 = {0.f, 0.f}, a2 = {0.f, 0.f}, a3 = {0.f, 0.f};
; #pragma unroll
;             for (int jp = 0; jp < ip; ++jp) {
;                 const f32x2_ ta = {tr[2 * jp], tr[2 * jp]}, tb = {tr[2 * jp + 1], tr[2 * jp + 1]};
;                 const f32x2_ va = {rv[jp][0], rv[jp][1]}, vb = {rv[jp][2], rv[jp][3]};
;                 if (jp & 1) { a2 += va * ta; a3 += vb * tb; } else { a0 += va * ta; a1 += vb * tb; }
;             }
;             const f32x2_ sum = (a0 + a1) + (a2 + a3);
;             const float t0 = (lane_o == i0 ? 1.f : 0.f) - sum[0];
;             tr[i0] = t0;
;             tr[i0 + 1] = (lane_o == i0 + 1 ? 1.f : 0.f) - sum[1] - rv[ip][1] * t0;
;         }
	v_pk_fma_f32 v[62:63], v[70:71], v[2:3], 0 op_sel_hi:[1,0,0]
	v_pk_fma_f32 v[62:63], v[72:73], v[2:3], v[62:63] op_sel:[0,1,0] op_sel_hi:[1,1,1]
	v_pk_fma_f32 v[62:63], v[74:75], v[4:5], v[62:63] op_sel_hi:[1,0,1]
	v_pk_fma_f32 v[62:63], v[76:77], v[4:5], v[62:63] op_sel:[0,1,0] op_sel_hi:[1,1,1]
	v_pk_fma_f32 v[62:63], v[82:83], v[10:11], v[62:63] op_sel_hi:[1,0,1]
	v_pk_fma_f32 v[62:63], v[84:85], v[10:11], v[62:63] op_sel:[0,1,0] op_sel_hi:[1,1,1]
	v_pk_fma_f32 v[62:63], v[78:79], v[8:9], v[62:63] op_sel_hi:[1,0,1]
	v_pk_fma_f32 v[62:63], v[80:81], v[8:9], v[62:63] op_sel:[0,1,0] op_sel_hi:[1,1,1]
	s_nop 1
	v_add_f32_dpp v62, v62, v62 quad_perm:[1,0,3,2] row_mask:0xf bank_mask:0xf bound_ctrl:1
	v_add_f32_dpp v63, v63, v63 quad_perm:[1,0,3,2] row_mask:0xf bank_mask:0xf bound_ctrl:1
	s_nop 0
	v_add_f32_dpp v62, v62, v62 quad_perm:[2,3,0,1] row_mask:0xf bank_mask:0xf bound_ctrl:1
	v_add_f32_dpp v63, v63, v63 quad_perm:[2,3,0,1] row_mask:0xf bank_mask:0xf bound_ctrl:1
	s_mov_b64 exec, s[4:5]
	v_pk_add_f32 v[10:11], v[10:11], v[62:63] neg_lo:[0,1] neg_hi:[0,1]
	v_fma_f32 v11, v83, v62, v11
	s_mov_b64 exec, -1
	ds_read_b128 v[70:73], v14 offset:7616
	ds_read_b128 v[74:77], v14 offset:7680
	ds_read_b128 v[78:81], v14 offset:7744
	ds_read_b128 v[82:85], v14 offset:7808
	s_waitcnt lgkmcnt(4)
	v_pk_fma_f32 v[62:63], v[122:123], v[2:3], 0 op_sel_hi:[1,0,0]
	v_pk_fma_f32 v[62:63], v[124:125], v[2:3], v[62:63] op_sel:[0,1,0] op_sel_hi:[1,1,1]
	v_pk_fma_f32 v[62:63], v[126:127], v[4:5], v[62:63] op_sel_hi:[1,0,1]
	v_pk_fma_f32 v[62:63], v[128:129], v[4:5], v[62:63] op_sel:[0,1,0] op_sel_hi:[1,1,1]
	v_pk_fma_f32 v[62:63], v[130:131], v[8:9], v[62:63] op_sel_hi:[1,0,1]
	v_pk_fma_f32 v[62:63], v[132:133], v[8:9], v[62:63] op_sel:[0,1,0] op_sel_hi:[1,1,1]
	v_pk_fma_f32 v[62:63], v[38:39], v[10:11], v[62:63] op_sel_hi:[1,0,1]
	v_pk_fma_f32 v[62:63], v[40:41], v[10:11], v[62:63] op_sel:[0,1,0] op_sel_hi:[1,1,1]
	s_nop 1
	v_add_f32_dpp v62, v62, v62 quad_perm:[1,0,3,2] row_mask:0xf bank_mask:0xf bound_ctrl:1
	v_add_f32_dpp v63, v63, v63 quad_perm:[1,0,3,2] row_mask:0xf bank_mask:0xf bound_ctrl:1
	s_nop 0
	v_add_f32_dpp v62, v62, v62 quad_perm:[2,3,0,1] row_mask:0xf bank_mask:0xf bound_ctrl:1
	v_add_f32_dpp v63, v63, v63 quad_perm:[2,3,0,1] row_mask:0xf bank_mask:0xf bound_ctrl:1
	s_mov_b64 exec, s[6:7]
	v_pk_add_f32 v[10:11], v[10:11], v[62:63] neg_lo:[0,1] neg_hi:[0,1]
	v_fma_f32 v11, v39, v62, v11
	s_mov_b64 exec, -1
	ds_read_b128 v[122:125], v14 offset:8160
	ds_read_b128 v[126:129], v14 offset:8224
	ds_read_b128 v[130:133], v14 offset:8288
	ds_read_b128 v[38:41], v14 offset:8352
	s_waitcnt lgkmcnt(4)
	v_pk_fma_f32 v[62:63], v[70:71], v[2:3], 0 op_sel_hi:[1,0,0]
	v_pk_fma_f32 v[62:63], v[72:73], v[2:3], v[62:63] op_sel:[0,1,0] op_sel_hi:[1,1,1]
	v_pk_fma_f32 v[62:63], v[74:75], v[4:5], v[62:63] op_sel_hi:[1,0,1]
	v_pk_fma_f32 v[62:63], v[76:77], v[4:5], v[62:63] op_sel:[0,1,0] op_sel_hi:[1,1,1]
	v_pk_fma_f32 v[62:63], v[78:79], v[8:9], v[62:63] op_sel_hi:[1,0,1]
	v_pk_fma_f32 v[62:63], v[80:81], v[8:9], v[62:63] op_sel:[0,1,0] op_sel_hi:[1,1,1]
	v_pk_fma_f32 v[62:63], v[82:83], v[10:11], v[62:63] op_sel_hi:[1,0,1]
	v_pk_fma_f32 v[62:63], v[84:85], v[10:11], v[62:63] op_sel:[0,1,0] op_sel_hi:[1,1,1]
	s_nop 1
	v_add_f32_dpp v62, v62, v62 quad_perm:[1,0,3,2] row_mask:0xf bank_mask:0xf bound_ctrl:1
	v_add_f32_dpp v63, v63, v63 quad_perm:[1,0,3,2] row_mask:0xf bank_mask:0xf bound_ctrl:1
	s_nop 0
	v_add_f32_dpp v62, v62, v62 quad_perm:[2,3,0,1] row_mask:0xf bank_mask:0xf bound_ctrl:1
	v_add_f32_dpp v63, v63, v63 quad_perm:[2,3,0,1] row_mask:0xf bank_mask:0xf bound_ctrl:1
	s_mov_b64 exec, s[8:9]
	v_pk_add_f32 v[10:11], v[10:11], v[62:63] neg_lo:[0,1] neg_hi:[0,1]
	v_fma_f32 v11, v83, v62, v11
	s_mov_b64 exec, -1
	ds_read_b128 v[70:73], v14 offset:8704
	ds_read_b128 v[74:77], v14 offset:8768
	ds_read_b128 v[78:81], v14 offset:8832
	ds_read_b128 v[82:85], v14 offset:8896
	ds_read_b128 v[86:89], v14 offset:8960
	s_waitcnt lgkmcnt(5)
	v_pk_fma_f32 v[62:63], v[122:123], v[2:3], 0 op_sel_hi:[1,0,0]
	v_pk_fma_f32 v[62:63], v[124:125], v[2:3], v[62:63] op_sel:[0,1,0] op_sel_hi:[1,1,1]
	v_pk_fma_f32 v[62:63], v[126:127], v[4:5], v[62:63] op_sel_hi:[1,0,1]
	v_pk_fma_f32 v[62:63], v[128:129], v[4:5], v[62:63] op_sel:[0,1,0] op_sel_hi:[1,1,1]
	v_pk_fma_f32 v[62:63], v[130:131], v[8:9], v[62:63] op_sel_hi:[1,0,1]
	v_pk_fma_f32 v[62:63], v[132:133], v[8:9], v[62:63] op_sel:[0,1,0] op_sel_hi:[1,1,1]
	v_pk_fma_f32 v[62:63], v[38:39], v[10:11], v[62:63] op_sel_hi:[1,0,1]
	v_pk_fma_f32 v[62:63], v[40:41], v[10:11], v[62:63] op_sel:[0,1,0] op_sel_hi:[1,1,1]
	s_nop 1
	v_add_f32_dpp v62, v62, v62 quad_perm:[1,0,3,2] row_mask:0xf bank_mask:0xf bound_ctrl:1
	v_add_f32_dpp v63, v63, v63 quad_perm:[1,0,3,2] row_mask:0xf bank_mask:0xf bound_ctrl:1
	s_nop 0
	v_add_f32_dpp v62, v62, v62 quad_perm:[2,3,0,1] row_mask:0xf bank_mask:0xf bound_ctrl:1
	v_add_f32_dpp v63, v63, v63 quad_perm:[2,3,0,1] row_mask:0xf bank_mask:0xf bound_ctrl:1
	s_mov_b64 exec, s[10:11]
	v_pk_add_f32 v[10:11], v[10:11], v[62:63] neg_lo:[0,1] neg_hi:[0,1]
	v_fma_f32 v11, v39, v62, v11
	s_mov_b64 exec, -1
	ds_read_b128 v[122:125], v14 offset:9248
	ds_read_b128 v[126:129], v14 offset:9312
	ds_read_b128 v[130:133], v14 offset:9376
	ds_read_b128 v[38:41], v14 offset:9440
	ds_read_b128 v[42:45], v14 offset:9504
	s_waitcnt lgkmcnt(5)
; #define LAS __attribute__((address_space(3)))
;     ...
; #pragma unroll
;         for (int ip = 0; ip < 32; ++ip) {
;             const int i0 = 2 * ip;
;             f32x4 rv[32];
; #pragma unroll
;             for (int jp = 0; jp <= ip; ++jp) rv[jp] = *(const LAS f32x4*)(Ad + ip * 136 + 4 * jp);
;             asm volatile("" : "+v"(lane_o) :: "memory");
;             f32x2_ a0 = {0.f, 0.f}, a1 = {0.f, 0.f}, a2 = {0.f, 0.f}, a3 = {0.f, 0.f};
; #pragma unroll
;             for (int jp = 0; jp < ip; ++jp) {
;                 const f32x2_ ta = {tr[2 * jp], tr[2 * jp]}, tb = {tr[2 * jp + 1], tr[2 * jp + 1]};
;                 const f32x2_ va = {rv[jp][0], rv[jp][1]}, vb = {rv[jp][2], rv[jp][3]};
;                 if (jp & 1) { a2 += va * ta; a3 += vb * tb; } else { a0 += va * ta; a1 += vb * tb; }
;             }
;             const f32x2_ sum = (a0 + a1) + (a2 + a3);
;             const float t0 = (lane_o == i0 ? 1.f : 0.f) - sum[0];
;             tr[i0] = t0;
;             tr[i0 + 1] = (lane_o == i0 + 1 ? 1.f : 0.f) - sum[1] - rv[ip][1] * t0;
;         }
	v_pk_fma_f32 v[62:63], v[70:71], v[2:3], 0 op_sel_hi:[1,0,0]
	v_pk_fma_f32 v[62:63], v[72:73], v[2:3], v[62:63] op_sel:[0,1,0] op_sel_hi:[1,1,1]
	v_pk_fma_f32 v[62:63], v[74:75], v[4:5], v[62:63] op_sel_hi:[1,0,1]
	v_pk_fma_f32 v[62:63], v[76:77], v[4:5], v[62:63] op_sel:[0,1,0] op_sel_hi:[1,1,1]
	v_pk_fma_f32 v[62:63], v[78:79], v[8:9], v[62:63] op_sel_hi:[1,0,1]
	v_pk_fma_f32 v[62:63], v[80:81], v[8:9], v[62:63] op_sel:[0,1,0] op_sel_hi:[1,1,1]
	v_pk_fma_f32 v[62:63], v[86:87], v[18:19], v[62:63] op_sel_hi:[1,0,1]
	v_pk_fma_f32 v[62:63], v[88:89], v[18:19], v[62:63] op_sel:[0,1,0] op_sel_hi:[1,1,1]
	v_pk_fma_f32 v[62:63], v[82:83], v[10:11], v[62:63] op_sel_hi:[1,0,1]
	v_pk_fma_f32 v[62:63], v[84:85], v[10:11], v[62:63] op_sel:[0,1,0] op_sel_hi:[1,1,1]
	s_nop 1
	v_add_f32_dpp v62, v62, v62 quad_perm:[1,0,3,2] row_mask:0xf bank_mask:0xf bound_ctrl:1
	v_add_f32_dpp v63, v63, v63 quad_perm:[1,0,3,2] row_mask:0xf bank_mask:0xf bound_ctrl:1
	s_nop 0
	v_add_f32_dpp v62, v62, v62 quad_perm:[2,3,0,1] row_mask:0xf bank_mask:0xf bound_ctrl:1
	v_add_f32_dpp v63, v63, v63 quad_perm:[2,3,0,1] row_mask:0xf bank_mask:0xf bound_ctrl:1
	s_mov_b64 exec, s[4:5]
	v_pk_add_f32 v[18:19], v[18:19], v[62:63] neg_lo:[0,1] neg_hi:[0,1]
	v_fma_f32 v19, v87, v62, v19
	s_mov_b64 exec, -1
	ds_read_b128 v[70:73], v14 offset:9792
	ds_read_b128 v[74:77], v14 offset:9856
	ds_read_b128 v[78:81], v14 offset:9920
	ds_read_b128 v[82:85], v14 offset:9984
	ds_read_b128 v[86:89], v14 offset:10048
	s_waitcnt lgkmcnt(5)
	v_pk_fma_f32 v[62:63], v[122:123], v[2:3], 0 op_sel_hi:[1,0,0]
	v_pk_fma_f32 v[62:63], v[124:125], v[2:3], v[62:63] op_sel:[0,1,0] op_sel_hi:[1,1,1]
	v_pk_fma_f32 v[62:63], v[126:127], v[4:5], v[62:63] op_sel_hi:[1,0,1]
	v_pk_fma_f32 v[62:63], v[128:129], v[4:5], v[62:63] op_sel:[0,1,0] op_sel_hi:[1,1,1]
	v_pk_fma_f32 v[62:63], v[130:131], v[8:9], v[62:63] op_sel_hi:[1,0,1]
	v_pk_fma_f32 v[62:63], v[132:133], v[8:9], v[62:63] op_sel:[0,1,0] op_sel_hi:[1,1,1]
	v_pk_fma_f32 v[62:63], v[38:39], v[10:11], v[62:63] op_sel_hi:[1,0,1]
	v_pk_fma_f32 v[62:63], v[40:41], v[10:11], v[62:63] op_sel:[0,1,0] op_sel_hi:[1,1,1]
	v_pk_fma_f32 v[62:63], v[42:43], v[18:19], v[62:63] op_sel_hi:[1,0,1]
	v_pk_fma_f32 v[62:63], v[44:45], v[18:19], v[62:63] op_sel:[0,1,0] op_sel_hi:[1,1,1]
	s_nop 1
	v_add_f32_dpp v62, v62, v62 quad_perm:[1,0,3,2] row_mask:0xf bank_mask:0xf bound_ctrl:1
	v_add_f32_dpp v63, v63, v63 quad_perm:[1,0,3,2] row_mask:0xf bank_mask:0xf bound_ctrl:1
	s_nop 0
	v_add_f32_dpp v62, v62, v62 quad_perm:[2,3,0,1] row_mask:0xf bank_mask:0xf bound_ctrl:1
	v_add_f32_dpp v63, v63, v63 quad_perm:[2,3,0,1] row_mask:0xf bank_mask:0xf bound_ctrl:1
	s_mov_b64 exec, s[6:7]
	v_pk_add_f32 v[18:19], v[18:19], v[62:63] neg_lo:[0,1] neg_hi:[0,1]
	v_fma_f32 v19, v43, v62, v19
	s_mov_b64 exec, -1
	ds_read_b128 v[122:125], v14 offset:10336
	ds_read_b128 v[126:129], v14 offset:10400
	ds_read_b128 v[130:133], v14 offset:10464
	ds_read_b128 v[38:41], v14 offset:10528
	ds_read_b128 v[42:45], v14 offset:10592
	s_waitcnt lgkmcnt(5)
	v_pk_fma_f32 v[62:63], v[70:71], v[2:3], 0 op_sel_hi:[1,0,0]
	v_pk_fma_f32 v[62:63], v[72:73], v[2:3], v[62:63] op_sel:[0,1,0] op_sel_hi:[1,1,1]
	v_pk_fma_f32 v[62:63], v[74:75], v[4:5], v[62:63] op_sel_hi:[1,0,1]
	v_pk_fma_f32 v[62:63], v[76:77], v[4:5], v[62:63] op_sel:[0,1,0] op_sel_hi:[1,1,1]
	v_pk_fma_f32 v[62:63], v[78:79], v[8:9], v[62:63] op_sel_hi:[1,0,1]
	v_pk_fma_f32 v[62:63], v[80:81], v[8:9], v[62:63] op_sel:[0,1,0] op_sel_hi:[1,1,1]
	v_pk_fma_f32 v[62:63], v[82:83], v[10:11], v[62:63] op_sel_hi:[1,0,1]
	v_pk_fma_f32 v[62:63], v[84:85], v[10:11], v[62:63] op_sel:[0,1,0] op_sel_hi:[1,1,1]
	v_pk_fma_f32 v[62:63], v[86:87], v[18:19], v[62:63] op_sel_hi:[1,0,1]
	v_pk_fma_f32 v[62:63], v[88:89], v[18:19], v[62:63] op_sel:[0,1,0] op_sel_hi:[1,1,1]
	s_nop 1
	v_add_f32_dpp v62, v62, v62 quad_perm:[1,0,3,2] row_mask:0xf bank_mask:0xf bound_ctrl:1
	v_add_f32_dpp v63, v63, v63 quad_perm:[1,0,3,2] row_mask:0xf bank_mask:0xf bound_ctrl:1
	s_nop 0
	v_add_f32_dpp v62, v62, v62 quad_perm:[2,3,0,1] row_mask:0xf bank_mask:0xf bound_ctrl:1
	v_add_f32_dpp v63, v63, v63 quad_perm:[2,3,0,1] row_mask:0xf bank_mask:0xf bound_ctrl:1
	s_mov_b64 exec, s[8:9]
	v_pk_add_f32 v[18:19], v[18:19], v[62:63] neg_lo:[0,1] neg_hi:[0,1]
	v_fma_f32 v19, v87, v62, v19
	s_mov_b64 exec, -1
	ds_read_b128 v[70:73], v14 offset:10880
	ds_read_b128 v[74:77], v14 offset:10944
	ds_read_b128 v[78:81], v14 offset:11008
	ds_read_b128 v[82:85], v14 offset:11072
	ds_read_b128 v[86:89], v14 offset:11136
	ds_read_b128 v[90:93], v14 offset:11200
	s_waitcnt lgkmcnt(6)
	v_pk_fma_f32 v[62:63], v[122:123], v[2:3], 0 op_sel_hi:[1,0,0]
	v_pk_fma_f32 v[62:63], v[124:125], v[2:3], v[62:63] op_sel:[0,1,0] op_sel_hi:[1,1,1]
	v_pk_fma_f32 v[62:63], v[126:127], v[4:5], v[62:63] op_sel_hi:[1,0,1]
	v_pk_fma_f32 v[62:63], v[128:129], v[4:5], v[62:63] op_sel:[0,1,0] op_sel_hi:[1,1,1]
	v_pk_fma_f32 v[62:63], v[130:131], v[8:9], v[62:63] op_sel_hi:[1,0,1]
	v_pk_fma_f32 v[62:63], v[132:133], v[8:9], v[62:63] op_sel:[0,1,0] op_sel_hi:[1,1,1]
	v_pk_fma_f32 v[62:63], v[38:39], v[10:11], v[62:63] op_sel_hi:[1,0,1]
	v_pk_fma_f32 v[62:63], v[40:41], v[10:11], v[62:63] op_sel:[0,1,0] op_sel_hi:[1,1,1]
	v_pk_fma_f32 v[62:63], v[42:43], v[18:19], v[62:63] op_sel_hi:[1,0,1]
	v_pk_fma_f32 v[62:63], v[44:45], v[18:19], v[62:63] op_sel:[0,1,0] op_sel_hi:[1,1,1]
	s_nop 1
	v_add_f32_dpp v62, v62, v62 quad_perm:[1,0,3,2] row_mask:0xf bank_mask:0xf bound_ctrl:1
	v_add_f32_dpp v63, v63, v63 quad_perm:[1,0,3,2] row_mask:0xf bank_mask:0xf bound_ctrl:1
	s_nop 0
	v_add_f32_dpp v62, v62, v62 quad_perm:[2,3,0,1] row_mask:0xf bank_mask:0xf bound_ctrl:1
	v_add_f32_dpp v63, v63, v63 quad_perm:[2,3,0,1] row_mask:0xf bank_mask:0xf bound_ctrl:1
	s_mov_b64 exec, s[10:11]
	v_pk_add_f32 v[18:19], v[18:19], v[62:63] neg_lo:[0,1] neg_hi:[0,1]
	v_fma_f32 v19, v43, v62, v19
	s_mov_b64 exec, -1
	ds_read_b128 v[122:125], v14 offset:11424
	ds_read_b128 v[126:129], v14 offset:11488
	ds_read_b128 v[130:133], v14 offset:11552
	ds_read_b128 v[38:41], v14 offset:11616
	ds_read_b128 v[42:45], v14 offset:11680
	ds_read_b128 v[46:49], v14 offset:11744
	s_waitcnt lgkmcnt(6)
; #define LAS __attribute__((address_space(3)))
;     ...
; #pragma unroll
;         for (int ip = 0; ip < 32; ++ip) {
;             const int i0 = 2 * ip;
;             f32x4 rv[32];
; #pragma unroll
;             for (int jp = 0; jp <= ip; ++jp) rv[jp] = *(const LAS f32x4*)(Ad + ip * 136 + 4 * jp);
;             asm volatile("" : "+v"(lane_o) :: "memory");
;             f32x2_ a0 = {0.f, 0.f}, a1 = {0.f, 0.f}, a2 = {0.f, 0.f}, a3 = {0.f, 0.f};
; #pragma unroll
;             for (int jp = 0; jp < ip; ++jp) {
;                 const f32x2_ ta = {tr[2 * jp], tr[2 * jp]}, tb = {tr[2 * jp + 1], tr[2 * jp + 1]};
;                 const f32x2_ va = {rv[jp][0], rv[jp][1]}, vb = {rv[jp][2], rv[jp][3]};
;                 if (jp & 1) { a2 += va * ta; a3 += vb * tb; } else { a0 += va * ta; a1 += vb * tb; }
;             }
;             const f32x2_ sum = (a0 + a1) + (a2 + a3);
;             const float t0 = (lane_o == i0 ? 1.f : 0.f) - sum[0];
;             tr[i0] = t0;
;             tr[i0 + 1] = (lane_o == i0 + 1 ? 1.f : 0.f) - sum[1] - rv[ip][1] * t0;
;         }
	v_pk_fma_f32 v[62:63], v[70:71], v[2:3], 0 op_sel_hi:[1,0,0]
	v_pk_fma_f32 v[62:63], v[72:73], v[2:3], v[62:63] op_sel:[0,1,0] op_sel_hi:[1,1,1]
	v_pk_fma_f32 v[62:63], v[74:75], v[4:5], v[62:63] op_sel_hi:[1,0,1]
	v_pk_fma_f32 v[62:63], v[76:77], v[4:5], v[62:63] op_sel:[0,1,0] op_sel_hi:[1,1,1]
	v_pk_fma_f32 v[62:63], v[78:79], v[8:9], v[62:63] op_sel_hi:[1,0,1]
	v_pk_fma_f32 v[62:63], v[80:81], v[8:9], v[62:63] op_sel:[0,1,0] op_sel_hi:[1,1,1]
	v_pk_fma_f32 v[62:63], v[82:83], v[10:11], v[62:63] op_sel_hi:[1,0,1]
	v_pk_fma_f32 v[62:63], v[84:85], v[10:11], v[62:63] op_sel:[0,1,0] op_sel_hi:[1,1,1]
	v_pk_fma_f32 v[62:63], v[90:91], v[50:51], v[62:63] op_sel_hi:[1,0,1]
	v_pk_fma_f32 v[62:63], v[92:93], v[50:51], v[62:63] op_sel:[0,1,0] op_sel_hi:[1,1,1]
	v_pk_fma_f32 v[62:63], v[86:87], v[18:19], v[62:63] op_sel_hi:[1,0,1]
	v_pk_fma_f32 v[62:63], v[88:89], v[18:19], v[62:63] op_sel:[0,1,0] op_sel_hi:[1,1,1]
	s_nop 1
	v_add_f32_dpp v62, v62, v62 quad_perm:[1,0,3,2] row_mask:0xf bank_mask:0xf bound_ctrl:1
	v_add_f32_dpp v63, v63, v63 quad_perm:[1,0,3,2] row_mask:0xf bank_mask:0xf bound_ctrl:1
	s_nop 0
	v_add_f32_dpp v62, v62, v62 quad_perm:[2,3,0,1] row_mask:0xf bank_mask:0xf bound_ctrl:1
	v_add_f32_dpp v63, v63, v63 quad_perm:[2,3,0,1] row_mask:0xf bank_mask:0xf bound_ctrl:1
	s_mov_b64 exec, s[4:5]
	v_pk_add_f32 v[50:51], v[50:51], v[62:63] neg_lo:[0,1] neg_hi:[0,1]
	v_fma_f32 v51, v91, v62, v51
	s_mov_b64 exec, -1
	ds_read_b128 v[70:73], v14 offset:11968
	ds_read_b128 v[74:77], v14 offset:12032
	ds_read_b128 v[78:81], v14 offset:12096
	ds_read_b128 v[82:85], v14 offset:12160
	ds_read_b128 v[86:89], v14 offset:12224
	ds_read_b128 v[90:93], v14 offset:12288
	s_waitcnt lgkmcnt(6)
	v_pk_fma_f32 v[62:63], v[122:123], v[2:3], 0 op_sel_hi:[1,0,0]
	v_pk_fma_f32 v[62:63], v[124:125], v[2:3], v[62:63] op_sel:[0,1,0] op_sel_hi:[1,1,1]
	v_pk_fma_f32 v[62:63], v[126:127], v[4:5], v[62:63] op_sel_hi:[1,0,1]
	v_pk_fma_f32 v[62:63], v[128:129], v[4:5], v[62:63] op_sel:[0,1,0] op_sel_hi:[1,1,1]
	v_pk_fma_f32 v[62:63], v[130:131], v[8:9], v[62:63] op_sel_hi:[1,0,1]
	v_pk_fma_f32 v[62:63], v[132:133], v[8:9], v[62:63] op_sel:[0,1,0] op_sel_hi:[1,1,1]
	v_pk_fma_f32 v[62:63], v[38:39], v[10:11], v[62:63] op_sel_hi:[1,0,1]
	v_pk_fma_f32 v[62:63], v[40:41], v[10:11], v[62:63] op_sel:[0,1,0] op_sel_hi:[1,1,1]
	v_pk_fma_f32 v[62:63], v[42:43], v[18:19], v[62:63] op_sel_hi:[1,0,1]
	v_pk_fma_f32 v[62:63], v[44:45], v[18:19], v[62:63] op_sel:[0,1,0] op_sel_hi:[1,1,1]
	v_pk_fma_f32 v[62:63], v[46:47], v[50:51], v[62:63] op_sel_hi:[1,0,1]
	v_pk_fma_f32 v[62:63], v[48:49], v[50:51], v[62:63] op_sel:[0,1,0] op_sel_hi:[1,1,1]
	s_nop 1
	v_add_f32_dpp v62, v62, v62 quad_perm:[1,0,3,2] row_mask:0xf bank_mask:0xf bound_ctrl:1
	v_add_f32_dpp v63, v63, v63 quad_perm:[1,0,3,2] row_mask:0xf bank_mask:0xf bound_ctrl:1
	s_nop 0
	v_add_f32_dpp v62, v62, v62 quad_perm:[2,3,0,1] row_mask:0xf bank_mask:0xf bound_ctrl:1
	v_add_f32_dpp v63, v63, v63 quad_perm:[2,3,0,1] row_mask:0xf bank_mask:0xf bound_ctrl:1
	s_mov_b64 exec, s[6:7]
	v_pk_add_f32 v[50:51], v[50:51], v[62:63] neg_lo:[0,1] neg_hi:[0,1]
	v_fma_f32 v51, v47, v62, v51
	s_mov_b64 exec, -1
	ds_read_b128 v[122:125], v14 offset:12512
	ds_read_b128 v[126:129], v14 offset:12576
	ds_read_b128 v[130:133], v14 offset:12640
	ds_read_b128 v[38:41], v14 offset:12704
	ds_read_b128 v[42:45], v14 offset:12768
	ds_read_b128 v[46:49], v14 offset:12832
	s_waitcnt lgkmcnt(6)
	v_pk_fma_f32 v[62:63], v[70:71], v[2:3], 0 op_sel_hi:[1,0,0]
	v_pk_fma_f32 v[62:63], v[72:73], v[2:3], v[62:63] op_sel:[0,1,0] op_sel_hi:[1,1,1]
	v_pk_fma_f32 v[62:63], v[74:75], v[4:5], v[62:63] op_sel_hi:[1,0,1]
	v_pk_fma_f32 v[62:63], v[76:77], v[4:5], v[62:63] op_sel:[0,1,0] op_sel_hi:[1,1,1]
	v_pk_fma_f32 v[62:63], v[78:79], v[8:9], v[62:63] op_sel_hi:[1,0,1]
	v_pk_fma_f32 v[62:63], v[80:81], v[8:9], v[62:63] op_sel:[0,1,0] op_sel_hi:[1,1,1]
	v_pk_fma_f32 v[62:63], v[82:83], v[10:11], v[62:63] op_sel_hi:[1,0,1]
	v_pk_fma_f32 v[62:63], v[84:85], v[10:11], v[62:63] op_sel:[0,1,0] op_sel_hi:[1,1,1]
	v_pk_fma_f32 v[62:63], v[86:87], v[18:19], v[62:63] op_sel_hi:[1,0,1]
	v_pk_fma_f32 v[62:63], v[88:89], v[18:19], v[62:63] op_sel:[0,1,0] op_sel_hi:[1,1,1]
	v_pk_fma_f32 v[62:63], v[90:91], v[50:51], v[62:63] op_sel_hi:[1,0,1]
	v_pk_fma_f32 v[62:63], v[92:93], v[50:51], v[62:63] op_sel:[0,1,0] op_sel_hi:[1,1,1]
	s_nop 1
	v_add_f32_dpp v62, v62, v62 quad_perm:[1,0,3,2] row_mask:0xf bank_mask:0xf bound_ctrl:1
	v_add_f32_dpp v63, v63, v63 quad_perm:[1,0,3,2] row_mask:0xf bank_mask:0xf bound_ctrl:1
	s_nop 0
	v_add_f32_dpp v62, v62, v62 quad_perm:[2,3,0,1] row_mask:0xf bank_mask:0xf bound_ctrl:1
	v_add_f32_dpp v63, v63, v63 quad_perm:[2,3,0,1] row_mask:0xf bank_mask:0xf bound_ctrl:1
	s_mov_b64 exec, s[8:9]
	v_pk_add_f32 v[50:51], v[50:51], v[62:63] neg_lo:[0,1] neg_hi:[0,1]
	v_fma_f32 v51, v91, v62, v51
	s_mov_b64 exec, -1
	ds_read_b128 v[70:73], v14 offset:13056
	ds_read_b128 v[74:77], v14 offset:13120
	ds_read_b128 v[78:81], v14 offset:13184
	ds_read_b128 v[82:85], v14 offset:13248
	ds_read_b128 v[86:89], v14 offset:13312
	ds_read_b128 v[90:93], v14 offset:13376
	ds_read_b128 v[94:97], v14 offset:13440
	s_waitcnt lgkmcnt(7)
; #define LAS __attribute__((address_space(3)))
;     ...
; #pragma unroll
;         for (int ip = 0; ip < 32; ++ip) {
;             const int i0 = 2 * ip;
;             f32x4 rv[32];
; #pragma unroll
;             for (int jp = 0; jp <= ip; ++jp) rv[jp] = *(const LAS f32x4*)(Ad + ip * 136 + 4 * jp);
;             asm volatile("" : "+v"(lane_o) :: "memory");
;             f32x2_ a0 = {0.f, 0.f}, a1 = {0.f, 0.f}, a2 = {0.f, 0.f}, a3 = {0.f, 0.f};
; #pragma unroll
;             for (int jp = 0; jp < ip; ++jp) {
;                 const f32x2_ ta = {tr[2 * jp], tr[2 * jp]}, tb = {tr[2 * jp + 1], tr[2 * jp + 1]};
;                 const f32x2_ va = {rv[jp][0], rv[jp][1]}, vb = {rv[jp][2], rv[jp][3]};
;                 if (jp & 1) { a2 += va * ta; a3 += vb * tb; } else { a0 += va * ta; a1 += vb * tb; }
;             }
;             const f32x2_ sum = (a0 + a1) + (a2 + a3);
;             const float t0 = (lane_o == i0 ? 1.f : 0.f) - sum[0];
;             tr[i0] = t0;
;             tr[i0 + 1] = (lane_o == i0 + 1 ? 1.f : 0.f) - sum[1] - rv[ip][1] * t0;
;         }
	v_pk_fma_f32 v[62:63], v[122:123], v[2:3], 0 op_sel_hi:[1,0,0]
	v_pk_fma_f32 v[62:63], v[124:125], v[2:3], v[62:63] op_sel:[0,1,0] op_sel_hi:[1,1,1]
	v_pk_fma_f32 v[62:63], v[126:127], v[4:5], v[62:63] op_sel_hi:[1,0,1]
	v_pk_fma_f32 v[62:63], v[128:129], v[4:5], v[62:63] op_sel:[0,1,0] op_sel_hi:[1,1,1]
	v_pk_fma_f32 v[62:63], v[130:131], v[8:9], v[62:63] op_sel_hi:[1,0,1]
	v_pk_fma_f32 v[62:63], v[132:133], v[8:9], v[62:63] op_sel:[0,1,0] op_sel_hi:[1,1,1]
	v_pk_fma_f32 v[62:63], v[38:39], v[10:11], v[62:63] op_sel_hi:[1,0,1]
	v_pk_fma_f32 v[62:63], v[40:41], v[10:11], v[62:63] op_sel:[0,1,0] op_sel_hi:[1,1,1]
	v_pk_fma_f32 v[62:63], v[42:43], v[18:19], v[62:63] op_sel_hi:[1,0,1]
	v_pk_fma_f32 v[62:63], v[44:45], v[18:19], v[62:63] op_sel:[0,1,0] op_sel_hi:[1,1,1]
	v_pk_fma_f32 v[62:63], v[46:47], v[50:51], v[62:63] op_sel_hi:[1,0,1]
	v_pk_fma_f32 v[62:63], v[48:49], v[50:51], v[62:63] op_sel:[0,1,0] op_sel_hi:[1,1,1]
	s_nop 1
	v_add_f32_dpp v62, v62, v62 quad_perm:[1,0,3,2] row_mask:0xf bank_mask:0xf bound_ctrl:1
	v_add_f32_dpp v63, v63, v63 quad_perm:[1,0,3,2] row_mask:0xf bank_mask:0xf bound_ctrl:1
	s_nop 0
	v_add_f32_dpp v62, v62, v62 quad_perm:[2,3,0,1] row_mask:0xf bank_mask:0xf bound_ctrl:1
	v_add_f32_dpp v63, v63, v63 quad_perm:[2,3,0,1] row_mask:0xf bank_mask:0xf bound_ctrl:1
	s_mov_b64 exec, s[10:11]
	v_pk_add_f32 v[50:51], v[50:51], v[62:63] neg_lo:[0,1] neg_hi:[0,1]
	v_fma_f32 v51, v47, v62, v51
	s_mov_b64 exec, -1
	ds_read_b128 v[122:125], v14 offset:13600
	ds_read_b128 v[126:129], v14 offset:13664
	ds_read_b128 v[130:133], v14 offset:13728
	ds_read_b128 v[38:41], v14 offset:13792
	ds_read_b128 v[42:45], v14 offset:13856
	ds_read_b128 v[46:49], v14 offset:13920
	ds_read_b128 v[102:105], v14 offset:13984
	s_waitcnt lgkmcnt(7)
	v_pk_fma_f32 v[62:63], v[70:71], v[2:3], 0 op_sel_hi:[1,0,0]
	v_pk_fma_f32 v[62:63], v[72:73], v[2:3], v[62:63] op_sel:[0,1,0] op_sel_hi:[1,1,1]
	v_pk_fma_f32 v[62:63], v[74:75], v[4:5], v[62:63] op_sel_hi:[1,0,1]
	v_pk_fma_f32 v[62:63], v[76:77], v[4:5], v[62:63] op_sel:[0,1,0] op_sel_hi:[1,1,1]
	v_pk_fma_f32 v[62:63], v[78:79], v[8:9], v[62:63] op_sel_hi:[1,0,1]
	v_pk_fma_f32 v[62:63], v[80:81], v[8:9], v[62:63] op_sel:[0,1,0] op_sel_hi:[1,1,1]
	v_pk_fma_f32 v[62:63], v[82:83], v[10:11], v[62:63] op_sel_hi:[1,0,1]
	v_pk_fma_f32 v[62:63], v[84:85], v[10:11], v[62:63] op_sel:[0,1,0] op_sel_hi:[1,1,1]
	v_pk_fma_f32 v[62:63], v[86:87], v[18:19], v[62:63] op_sel_hi:[1,0,1]
	v_pk_fma_f32 v[62:63], v[88:89], v[18:19], v[62:63] op_sel:[0,1,0] op_sel_hi:[1,1,1]
	v_pk_fma_f32 v[62:63], v[94:95], v[54:55], v[62:63] op_sel_hi:[1,0,1]
	v_pk_fma_f32 v[62:63], v[96:97], v[54:55], v[62:63] op_sel:[0,1,0] op_sel_hi:[1,1,1]
	v_pk_fma_f32 v[62:63], v[90:91], v[50:51], v[62:63] op_sel_hi:[1,0,1]
	v_pk_fma_f32 v[62:63], v[92:93], v[50:51], v[62:63] op_sel:[0,1,0] op_sel_hi:[1,1,1]
	s_nop 1
	v_add_f32_dpp v62, v62, v62 quad_perm:[1,0,3,2] row_mask:0xf bank_mask:0xf bound_ctrl:1
	v_add_f32_dpp v63, v63, v63 quad_perm:[1,0,3,2] row_mask:0xf bank_mask:0xf bound_ctrl:1
	s_nop 0
	v_add_f32_dpp v62, v62, v62 quad_perm:[2,3,0,1] row_mask:0xf bank_mask:0xf bound_ctrl:1
	v_add_f32_dpp v63, v63, v63 quad_perm:[2,3,0,1] row_mask:0xf bank_mask:0xf bound_ctrl:1
	s_mov_b64 exec, s[4:5]
	v_pk_add_f32 v[54:55], v[54:55], v[62:63] neg_lo:[0,1] neg_hi:[0,1]
	v_fma_f32 v55, v95, v62, v55
	s_mov_b64 exec, -1
	ds_read_b128 v[70:73], v14 offset:14144
	ds_read_b128 v[74:77], v14 offset:14208
	ds_read_b128 v[78:81], v14 offset:14272
	ds_read_b128 v[82:85], v14 offset:14336
	ds_read_b128 v[86:89], v14 offset:14400
	ds_read_b128 v[90:93], v14 offset:14464
	ds_read_b128 v[94:97], v14 offset:14528
	s_waitcnt lgkmcnt(7)
	v_pk_fma_f32 v[62:63], v[122:123], v[2:3], 0 op_sel_hi:[1,0,0]
	v_pk_fma_f32 v[62:63], v[124:125], v[2:3], v[62:63] op_sel:[0,1,0] op_sel_hi:[1,1,1]
	v_pk_fma_f32 v[62:63], v[126:127], v[4:5], v[62:63] op_sel_hi:[1,0,1]
	v_pk_fma_f32 v[62:63], v[128:129], v[4:5], v[62:63] op_sel:[0,1,0] op_sel_hi:[1,1,1]
	v_pk_fma_f32 v[62:63], v[130:131], v[8:9], v[62:63] op_sel_hi:[1,0,1]
	v_pk_fma_f32 v[62:63], v[132:133], v[8:9], v[62:63] op_sel:[0,1,0] op_sel_hi:[1,1,1]
	v_pk_fma_f32 v[62:63], v[38:39], v[10:11], v[62:63] op_sel_hi:[1,0,1]
	v_pk_fma_f32 v[62:63], v[40:41], v[10:11], v[62:63] op_sel:[0,1,0] op_sel_hi:[1,1,1]
	v_pk_fma_f32 v[62:63], v[42:43], v[18:19], v[62:63] op_sel_hi:[1,0,1]
	v_pk_fma_f32 v[62:63], v[44:45], v[18:19], v[62:63] op_sel:[0,1,0] op_sel_hi:[1,1,1]
	v_pk_fma_f32 v[62:63], v[46:47], v[50:51], v[62:63] op_sel_hi:[1,0,1]
	v_pk_fma_f32 v[62:63], v[48:49], v[50:51], v[62:63] op_sel:[0,1,0] op_sel_hi:[1,1,1]
	v_pk_fma_f32 v[62:63], v[102:103], v[54:55], v[62:63] op_sel_hi:[1,0,1]
	v_pk_fma_f32 v[62:63], v[104:105], v[54:55], v[62:63] op_sel:[0,1,0] op_sel_hi:[1,1,1]
	s_nop 1
	v_add_f32_dpp v62, v62, v62 quad_perm:[1,0,3,2] row_mask:0xf bank_mask:0xf bound_ctrl:1
	v_add_f32_dpp v63, v63, v63 quad_perm:[1,0,3,2] row_mask:0xf bank_mask:0xf bound_ctrl:1
	s_nop 0
	v_add_f32_dpp v62, v62, v62 quad_perm:[2,3,0,1] row_mask:0xf bank_mask:0xf bound_ctrl:1
	v_add_f32_dpp v63, v63, v63 quad_perm:[2,3,0,1] row_mask:0xf bank_mask:0xf bound_ctrl:1
	s_mov_b64 exec, s[6:7]
	v_pk_add_f32 v[54:55], v[54:55], v[62:63] neg_lo:[0,1] neg_hi:[0,1]
	v_fma_f32 v55, v103, v62, v55
	s_mov_b64 exec, -1
	ds_read_b128 v[122:125], v14 offset:14688
	ds_read_b128 v[126:129], v14 offset:14752
	ds_read_b128 v[130:133], v14 offset:14816
	ds_read_b128 v[38:41], v14 offset:14880
	ds_read_b128 v[42:45], v14 offset:14944
	ds_read_b128 v[46:49], v14 offset:15008
	ds_read_b128 v[102:105], v14 offset:15072
	s_waitcnt lgkmcnt(7)
; #define LAS __attribute__((address_space(3)))
;     ...
; #pragma unroll
;         for (int ip = 0; ip < 32; ++ip) {
;             const int i0 = 2 * ip;
;             f32x4 rv[32];
; #pragma unroll
;             for (int jp = 0; jp <= ip; ++jp) rv[jp] = *(const LAS f32x4*)(Ad + ip * 136 + 4 * jp);
;             asm volatile("" : "+v"(lane_o) :: "memory");
;             f32x2_ a0 = {0.f, 0.f}, a1 = {0.f, 0.f}, a2 = {0.f, 0.f}, a3 = {0.f, 0.f};
; #pragma unroll
;             for (int jp = 0; jp < ip; ++jp) {
;                 const f32x2_ ta = {tr[2 * jp], tr[2 * jp]}, tb = {tr[2 * jp + 1], tr[2 * jp + 1]};
;                 const f32x2_ va = {rv[jp][0], rv[jp][1]}, vb = {rv[jp][2], rv[jp][3]};
;                 if (jp & 1) { a2 += va * ta; a3 += vb * tb; } else { a0 += va * ta; a1 += vb * tb; }
;             }
;             const f32x2_ sum = (a0 + a1) + (a2 + a3);
;             const float t0 = (lane_o == i0 ? 1.f : 0.f) - sum[0];
;             tr[i0] = t0;
;             tr[i0 + 1] = (lane_o == i0 + 1 ? 1.f : 0.f) - sum[1] - rv[ip][1] * t0;
;         }
	v_pk_fma_f32 v[62:63], v[70:71], v[2:3], 0 op_sel_hi:[1,0,0]
	v_pk_fma_f32 v[62:63], v[72:73], v[2:3], v[62:63] op_sel:[0,1,0] op_sel_hi:[1,1,1]
	v_pk_fma_f32 v[62:63], v[74:75], v[4:5], v[62:63] op_sel_hi:[1,0,1]
	v_pk_fma_f32 v[62:63], v[76:77], v[4:5], v[62:63] op_sel:[0,1,0] op_sel_hi:[1,1,1]
	v_pk_fma_f32 v[62:63], v[78:79], v[8:9], v[62:63] op_sel_hi:[1,0,1]
	v_pk_fma_f32 v[62:63], v[80:81], v[8:9], v[62:63] op_sel:[0,1,0] op_sel_hi:[1,1,1]
	v_pk_fma_f32 v[62:63], v[82:83], v[10:11], v[62:63] op_sel_hi:[1,0,1]
	v_pk_fma_f32 v[62:63], v[84:85], v[10:11], v[62:63] op_sel:[0,1,0] op_sel_hi:[1,1,1]
	v_pk_fma_f32 v[62:63], v[86:87], v[18:19], v[62:63] op_sel_hi:[1,0,1]
	v_pk_fma_f32 v[62:63], v[88:89], v[18:19], v[62:63] op_sel:[0,1,0] op_sel_hi:[1,1,1]
	v_pk_fma_f32 v[62:63], v[90:91], v[50:51], v[62:63] op_sel_hi:[1,0,1]
	v_pk_fma_f32 v[62:63], v[92:93], v[50:51], v[62:63] op_sel:[0,1,0] op_sel_hi:[1,1,1]
	v_pk_fma_f32 v[62:63], v[94:95], v[54:55], v[62:63] op_sel_hi:[1,0,1]
	v_pk_fma_f32 v[62:63], v[96:97], v[54:55], v[62:63] op_sel:[0,1,0] op_sel_hi:[1,1,1]
	s_nop 1
	v_add_f32_dpp v62, v62, v62 quad_perm:[1,0,3,2] row_mask:0xf bank_mask:0xf bound_ctrl:1
	v_add_f32_dpp v63, v63, v63 quad_perm:[1,0,3,2] row_mask:0xf bank_mask:0xf bound_ctrl:1
	s_nop 0
	v_add_f32_dpp v62, v62, v62 quad_perm:[2,3,0,1] row_mask:0xf bank_mask:0xf bound_ctrl:1
	v_add_f32_dpp v63, v63, v63 quad_perm:[2,3,0,1] row_mask:0xf bank_mask:0xf bound_ctrl:1
	s_mov_b64 exec, s[8:9]
	v_pk_add_f32 v[54:55], v[54:55], v[62:63] neg_lo:[0,1] neg_hi:[0,1]
	v_fma_f32 v55, v95, v62, v55
	s_mov_b64 exec, -1
	ds_read_b128 v[70:73], v14 offset:15232
	ds_read_b128 v[74:77], v14 offset:15296
	ds_read_b128 v[78:81], v14 offset:15360
	ds_read_b128 v[82:85], v14 offset:15424
	ds_read_b128 v[86:89], v14 offset:15488
	ds_read_b128 v[90:93], v14 offset:15552
	ds_read_b128 v[94:97], v14 offset:15616
	ds_read_b128 v[98:101], v14 offset:15680
	s_waitcnt lgkmcnt(8)
	v_pk_fma_f32 v[62:63], v[122:123], v[2:3], 0 op_sel_hi:[1,0,0]
	v_pk_fma_f32 v[62:63], v[124:125], v[2:3], v[62:63] op_sel:[0,1,0] op_sel_hi:[1,1,1]
	v_pk_fma_f32 v[62:63], v[126:127], v[4:5], v[62:63] op_sel_hi:[1,0,1]
	v_pk_fma_f32 v[62:63], v[128:129], v[4:5], v[62:63] op_sel:[0,1,0] op_sel_hi:[1,1,1]
	v_pk_fma_f32 v[62:63], v[130:131], v[8:9], v[62:63] op_sel_hi:[1,0,1]
	v_pk_fma_f32 v[62:63], v[132:133], v[8:9], v[62:63] op_sel:[0,1,0] op_sel_hi:[1,1,1]
	v_pk_fma_f32 v[62:63], v[38:39], v[10:11], v[62:63] op_sel_hi:[1,0,1]
	v_pk_fma_f32 v[62:63], v[40:41], v[10:11], v[62:63] op_sel:[0,1,0] op_sel_hi:[1,1,1]
	v_pk_fma_f32 v[62:63], v[42:43], v[18:19], v[62:63] op_sel_hi:[1,0,1]
	v_pk_fma_f32 v[62:63], v[44:45], v[18:19], v[62:63] op_sel:[0,1,0] op_sel_hi:[1,1,1]
	v_pk_fma_f32 v[62:63], v[46:47], v[50:51], v[62:63] op_sel_hi:[1,0,1]
	v_pk_fma_f32 v[62:63], v[48:49], v[50:51], v[62:63] op_sel:[0,1,0] op_sel_hi:[1,1,1]
	v_pk_fma_f32 v[62:63], v[102:103], v[54:55], v[62:63] op_sel_hi:[1,0,1]
	v_pk_fma_f32 v[62:63], v[104:105], v[54:55], v[62:63] op_sel:[0,1,0] op_sel_hi:[1,1,1]
	s_nop 1
	v_add_f32_dpp v62, v62, v62 quad_perm:[1,0,3,2] row_mask:0xf bank_mask:0xf bound_ctrl:1
	v_add_f32_dpp v63, v63, v63 quad_perm:[1,0,3,2] row_mask:0xf bank_mask:0xf bound_ctrl:1
	s_nop 0
	v_add_f32_dpp v62, v62, v62 quad_perm:[2,3,0,1] row_mask:0xf bank_mask:0xf bound_ctrl:1
	v_add_f32_dpp v63, v63, v63 quad_perm:[2,3,0,1] row_mask:0xf bank_mask:0xf bound_ctrl:1
	s_mov_b64 exec, s[10:11]
	v_pk_add_f32 v[54:55], v[54:55], v[62:63] neg_lo:[0,1] neg_hi:[0,1]
	v_fma_f32 v55, v103, v62, v55
	s_mov_b64 exec, -1
	ds_read_b128 v[122:125], v14 offset:15776
	ds_read_b128 v[126:129], v14 offset:15840
	ds_read_b128 v[130:133], v14 offset:15904
	ds_read_b128 v[38:41], v14 offset:15968
	ds_read_b128 v[42:45], v14 offset:16032
	ds_read_b128 v[46:49], v14 offset:16096
	ds_read_b128 v[102:105], v14 offset:16160
	ds_read_b128 v[242:245], v14 offset:16224
	s_waitcnt lgkmcnt(8)
	v_pk_fma_f32 v[62:63], v[70:71], v[2:3], 0 op_sel_hi:[1,0,0]
	v_pk_fma_f32 v[62:63], v[72:73], v[2:3], v[62:63] op_sel:[0,1,0] op_sel_hi:[1,1,1]
	v_pk_fma_f32 v[62:63], v[74:75], v[4:5], v[62:63] op_sel_hi:[1,0,1]
	v_pk_fma_f32 v[62:63], v[76:77], v[4:5], v[62:63] op_sel:[0,1,0] op_sel_hi:[1,1,1]
	v_pk_fma_f32 v[62:63], v[78:79], v[8:9], v[62:63] op_sel_hi:[1,0,1]
	v_pk_fma_f32 v[62:63], v[80:81], v[8:9], v[62:63] op_sel:[0,1,0] op_sel_hi:[1,1,1]
	v_pk_fma_f32 v[62:63], v[82:83], v[10:11], v[62:63] op_sel_hi:[1,0,1]
	v_pk_fma_f32 v[62:63], v[84:85], v[10:11], v[62:63] op_sel:[0,1,0] op_sel_hi:[1,1,1]
	v_pk_fma_f32 v[62:63], v[86:87], v[18:19], v[62:63] op_sel_hi:[1,0,1]
	v_pk_fma_f32 v[62:63], v[88:89], v[18:19], v[62:63] op_sel:[0,1,0] op_sel_hi:[1,1,1]
	v_pk_fma_f32 v[62:63], v[90:91], v[50:51], v[62:63] op_sel_hi:[1,0,1]
	v_pk_fma_f32 v[62:63], v[92:93], v[50:51], v[62:63] op_sel:[0,1,0] op_sel_hi:[1,1,1]
	v_pk_fma_f32 v[62:63], v[98:99], v[58:59], v[62:63] op_sel_hi:[1,0,1]
	v_pk_fma_f32 v[62:63], v[100:101], v[58:59], v[62:63] op_sel:[0,1,0] op_sel_hi:[1,1,1]
	v_pk_fma_f32 v[62:63], v[94:95], v[54:55], v[62:63] op_sel_hi:[1,0,1]
	v_pk_fma_f32 v[62:63], v[96:97], v[54:55], v[62:63] op_sel:[0,1,0] op_sel_hi:[1,1,1]
	s_nop 1
	v_add_f32_dpp v62, v62, v62 quad_perm:[1,0,3,2] row_mask:0xf bank_mask:0xf bound_ctrl:1
	v_add_f32_dpp v63, v63, v63 quad_perm:[1,0,3,2] row_mask:0xf bank_mask:0xf bound_ctrl:1
	s_nop 0
	v_add_f32_dpp v62, v62, v62 quad_perm:[2,3,0,1] row_mask:0xf bank_mask:0xf bound_ctrl:1
	v_add_f32_dpp v63, v63, v63 quad_perm:[2,3,0,1] row_mask:0xf bank_mask:0xf bound_ctrl:1
	s_mov_b64 exec, s[4:5]
	v_pk_add_f32 v[58:59], v[58:59], v[62:63] neg_lo:[0,1] neg_hi:[0,1]
	v_fma_f32 v59, v99, v62, v59
	s_mov_b64 exec, -1
	ds_read_b128 v[70:73], v14 offset:16320
	ds_read_b128 v[74:77], v14 offset:16384
	ds_read_b128 v[78:81], v14 offset:16448
	ds_read_b128 v[82:85], v14 offset:16512
	ds_read_b128 v[86:89], v14 offset:16576
	ds_read_b128 v[90:93], v14 offset:16640
	ds_read_b128 v[94:97], v14 offset:16704
	ds_read_b128 v[98:101], v14 offset:16768
	s_waitcnt lgkmcnt(8)
; #define LAS __attribute__((address_space(3)))
;     ...
; #pragma unroll
;         for (int ip = 0; ip < 32; ++ip) {
;             const int i0 = 2 * ip;
;             f32x4 rv[32];
; #pragma unroll
;             for (int jp = 0; jp <= ip; ++jp) rv[jp] = *(const LAS f32x4*)(Ad + ip * 136 + 4 * jp);
;             asm volatile("" : "+v"(lane_o) :: "memory");
;             f32x2_ a0 = {0.f, 0.f}, a1 = {0.f, 0.f}, a2 = {0.f, 0.f}, a3 = {0.f, 0.f};
; #pragma unroll
;             for (int jp = 0; jp < ip; ++jp) {
;                 const f32x2_ ta = {tr[2 * jp], tr[2 * jp]}, tb = {tr[2 * jp + 1], tr[2 * jp + 1]};
;                 const f32x2_ va = {rv[jp][0], rv[jp][1]}, vb = {rv[jp][2], rv[jp][3]};
;                 if (jp & 1) { a2 += va * ta; a3 += vb * tb; } else { a0 += va * ta; a1 += vb * tb; }
;             }
;             const f32x2_ sum = (a0 + a1) + (a2 + a3);
;             const float t0 = (lane_o == i0 ? 1.f : 0.f) - sum[0];
;             tr[i0] = t0;
;             tr[i0 + 1] = (lane_o == i0 + 1 ? 1.f : 0.f) - sum[1] - rv[ip][1] * t0;
;         }
	v_pk_fma_f32 v[62:63], v[122:123], v[2:3], 0 op_sel_hi:[1,0,0]
	v_pk_fma_f32 v[62:63], v[124:125], v[2:3], v[62:63] op_sel:[0,1,0] op_sel_hi:[1,1,1]
	v_pk_fma_f32 v[62:63], v[126:127], v[4:5], v[62:63] op_sel_hi:[1,0,1]
	v_pk_fma_f32 v[62:63], v[128:129], v[4:5], v[62:63] op_sel:[0,1,0] op_sel_hi:[1,1,1]
	v_pk_fma_f32 v[62:63], v[130:131], v[8:9], v[62:63] op_sel_hi:[1,0,1]
	v_pk_fma_f32 v[62:63], v[132:133], v[8:9], v[62:63] op_sel:[0,1,0] op_sel_hi:[1,1,1]
	v_pk_fma_f32 v[62:63], v[38:39], v[10:11], v[62:63] op_sel_hi:[1,0,1]
	v_pk_fma_f32 v[62:63], v[40:41], v[10:11], v[62:63] op_sel:[0,1,0] op_sel_hi:[1,1,1]
	v_pk_fma_f32 v[62:63], v[42:43], v[18:19], v[62:63] op_sel_hi:[1,0,1]
	v_pk_fma_f32 v[62:63], v[44:45], v[18:19], v[62:63] op_sel:[0,1,0] op_sel_hi:[1,1,1]
	v_pk_fma_f32 v[62:63], v[46:47], v[50:51], v[62:63] op_sel_hi:[1,0,1]
	v_pk_fma_f32 v[62:63], v[48:49], v[50:51], v[62:63] op_sel:[0,1,0] op_sel_hi:[1,1,1]
	v_pk_fma_f32 v[62:63], v[102:103], v[54:55], v[62:63] op_sel_hi:[1,0,1]
	v_pk_fma_f32 v[62:63], v[104:105], v[54:55], v[62:63] op_sel:[0,1,0] op_sel_hi:[1,1,1]
	v_pk_fma_f32 v[62:63], v[242:243], v[58:59], v[62:63] op_sel_hi:[1,0,1]
	v_pk_fma_f32 v[62:63], v[244:245], v[58:59], v[62:63] op_sel:[0,1,0] op_sel_hi:[1,1,1]
	s_nop 1
	v_add_f32_dpp v62, v62, v62 quad_perm:[1,0,3,2] row_mask:0xf bank_mask:0xf bound_ctrl:1
	v_add_f32_dpp v63, v63, v63 quad_perm:[1,0,3,2] row_mask:0xf bank_mask:0xf bound_ctrl:1
	s_nop 0
	v_add_f32_dpp v62, v62, v62 quad_perm:[2,3,0,1] row_mask:0xf bank_mask:0xf bound_ctrl:1
	v_add_f32_dpp v63, v63, v63 quad_perm:[2,3,0,1] row_mask:0xf bank_mask:0xf bound_ctrl:1
	s_mov_b64 exec, s[6:7]
	v_pk_add_f32 v[58:59], v[58:59], v[62:63] neg_lo:[0,1] neg_hi:[0,1]
	v_fma_f32 v59, v243, v62, v59
	s_mov_b64 exec, -1
	ds_read_b128 v[122:125], v14 offset:16864
	ds_read_b128 v[126:129], v14 offset:16928
	ds_read_b128 v[130:133], v14 offset:16992
	ds_read_b128 v[38:41], v14 offset:17056
	ds_read_b128 v[42:45], v14 offset:17120
	ds_read_b128 v[46:49], v14 offset:17184
	ds_read_b128 v[102:105], v14 offset:17248
	ds_read_b128 v[242:245], v14 offset:17312
	s_waitcnt lgkmcnt(8)
	v_pk_fma_f32 v[62:63], v[70:71], v[2:3], 0 op_sel_hi:[1,0,0]
	v_pk_fma_f32 v[62:63], v[72:73], v[2:3], v[62:63] op_sel:[0,1,0] op_sel_hi:[1,1,1]
	v_pk_fma_f32 v[62:63], v[74:75], v[4:5], v[62:63] op_sel_hi:[1,0,1]
	v_pk_fma_f32 v[62:63], v[76:77], v[4:5], v[62:63] op_sel:[0,1,0] op_sel_hi:[1,1,1]
	v_pk_fma_f32 v[62:63], v[78:79], v[8:9], v[62:63] op_sel_hi:[1,0,1]
	v_pk_fma_f32 v[62:63], v[80:81], v[8:9], v[62:63] op_sel:[0,1,0] op_sel_hi:[1,1,1]
	v_pk_fma_f32 v[62:63], v[82:83], v[10:11], v[62:63] op_sel_hi:[1,0,1]
	v_pk_fma_f32 v[62:63], v[84:85], v[10:11], v[62:63] op_sel:[0,1,0] op_sel_hi:[1,1,1]
	v_pk_fma_f32 v[62:63], v[86:87], v[18:19], v[62:63] op_sel_hi:[1,0,1]
	v_pk_fma_f32 v[62:63], v[88:89], v[18:19], v[62:63] op_sel:[0,1,0] op_sel_hi:[1,1,1]
	v_pk_fma_f32 v[62:63], v[90:91], v[50:51], v[62:63] op_sel_hi:[1,0,1]
	v_pk_fma_f32 v[62:63], v[92:93], v[50:51], v[62:63] op_sel:[0,1,0] op_sel_hi:[1,1,1]
	v_pk_fma_f32 v[62:63], v[94:95], v[54:55], v[62:63] op_sel_hi:[1,0,1]
	v_pk_fma_f32 v[62:63], v[96:97], v[54:55], v[62:63] op_sel:[0,1,0] op_sel_hi:[1,1,1]
	v_pk_fma_f32 v[62:63], v[98:99], v[58:59], v[62:63] op_sel_hi:[1,0,1]
	v_pk_fma_f32 v[62:63], v[100:101], v[58:59], v[62:63] op_sel:[0,1,0] op_sel_hi:[1,1,1]
	s_nop 1
	v_add_f32_dpp v62, v62, v62 quad_perm:[1,0,3,2] row_mask:0xf bank_mask:0xf bound_ctrl:1
	v_add_f32_dpp v63, v63, v63 quad_perm:[1,0,3,2] row_mask:0xf bank_mask:0xf bound_ctrl:1
	s_nop 0
	v_add_f32_dpp v62, v62, v62 quad_perm:[2,3,0,1] row_mask:0xf bank_mask:0xf bound_ctrl:1
	v_add_f32_dpp v63, v63, v63 quad_perm:[2,3,0,1] row_mask:0xf bank_mask:0xf bound_ctrl:1
	s_mov_b64 exec, s[8:9]
	v_pk_add_f32 v[58:59], v[58:59], v[62:63] neg_lo:[0,1] neg_hi:[0,1]
	v_fma_f32 v59, v99, v62, v59
	s_mov_b64 exec, -1
	s_waitcnt lgkmcnt(0)
	v_pk_fma_f32 v[62:63], v[122:123], v[2:3], 0 op_sel_hi:[1,0,0]
	v_pk_fma_f32 v[62:63], v[124:125], v[2:3], v[62:63] op_sel:[0,1,0] op_sel_hi:[1,1,1]
	v_pk_fma_f32 v[62:63], v[126:127], v[4:5], v[62:63] op_sel_hi:[1,0,1]
	v_pk_fma_f32 v[62:63], v[128:129], v[4:5], v[62:63] op_sel:[0,1,0] op_sel_hi:[1,1,1]
	v_pk_fma_f32 v[62:63], v[130:131], v[8:9], v[62:63] op_sel_hi:[1,0,1]
	v_pk_fma_f32 v[62:63], v[132:133], v[8:9], v[62:63] op_sel:[0,1,0] op_sel_hi:[1,1,1]
	v_pk_fma_f32 v[62:63], v[38:39], v[10:11], v[62:63] op_sel_hi:[1,0,1]
	v_pk_fma_f32 v[62:63], v[40:41], v[10:11], v[62:63] op_sel:[0,1,0] op_sel_hi:[1,1,1]
	v_pk_fma_f32 v[62:63], v[42:43], v[18:19], v[62:63] op_sel_hi:[1,0,1]
	v_pk_fma_f32 v[62:63], v[44:45], v[18:19], v[62:63] op_sel:[0,1,0] op_sel_hi:[1,1,1]
	v_pk_fma_f32 v[62:63], v[46:47], v[50:51], v[62:63] op_sel_hi:[1,0,1]
	v_pk_fma_f32 v[62:63], v[48:49], v[50:51], v[62:63] op_sel:[0,1,0] op_sel_hi:[1,1,1]
	v_pk_fma_f32 v[62:63], v[102:103], v[54:55], v[62:63] op_sel_hi:[1,0,1]
	v_pk_fma_f32 v[62:63], v[104:105], v[54:55], v[62:63] op_sel:[0,1,0] op_sel_hi:[1,1,1]
	v_pk_fma_f32 v[62:63], v[242:243], v[58:59], v[62:63] op_sel_hi:[1,0,1]
	v_pk_fma_f32 v[62:63], v[244:245], v[58:59], v[62:63] op_sel:[0,1,0] op_sel_hi:[1,1,1]
	s_nop 1
	v_add_f32_dpp v62, v62, v62 quad_perm:[1,0,3,2] row_mask:0xf bank_mask:0xf bound_ctrl:1
	v_add_f32_dpp v63, v63, v63 quad_perm:[1,0,3,2] row_mask:0xf bank_mask:0xf bound_ctrl:1
	s_nop 0
	v_add_f32_dpp v62, v62, v62 quad_perm:[2,3,0,1] row_mask:0xf bank_mask:0xf bound_ctrl:1
	v_add_f32_dpp v63, v63, v63 quad_perm:[2,3,0,1] row_mask:0xf bank_mask:0xf bound_ctrl:1
	s_mov_b64 exec, s[10:11]
	v_pk_add_f32 v[58:59], v[58:59], v[62:63] neg_lo:[0,1] neg_hi:[0,1]
	v_fma_f32 v59, v243, v62, v59
	s_mov_b64 exec, -1
	s_branch .Lfs_outsel
; #define LAS __attribute__((address_space(3)))
;     ...
; #pragma unroll
;         for (int ip = 0; ip < 32; ++ip) {
;             const int i0 = 2 * ip;
;             f32x4 rv[32];
; #pragma unroll
;             for (int jp = 0; jp <= ip; ++jp) rv[jp] = *(const LAS f32x4*)(Ad + ip * 136 + 4 * jp);
;             asm volatile("" : "+v"(lane_o) :: "memory");
;             f32x2_ a0 = {0.f, 0.f}, a1 = {0.f, 0.f}, a2 = {0.f, 0.f}, a3 = {0.f, 0.f};
; #pragma unroll
;             for (int jp = 0; jp < ip; ++jp) {
;                 const f32x2_ ta = {tr[2 * jp], tr[2 * jp]}, tb = {tr[2 * jp + 1], tr[2 * jp + 1]};
;                 const f32x2_ va = {rv[jp][0], rv[jp][1]}, vb = {rv[jp][2], rv[jp][3]};
;                 if (jp & 1) { a2 += va * ta; a3 += vb * tb; } else { a0 += va * ta; a1 += vb * tb; }
;             }
;             const f32x2_ sum = (a0 + a1) + (a2 + a3);
;             const float t0 = (lane_o == i0 ? 1.f : 0.f) - sum[0];
;             tr[i0] = t0;
;             tr[i0 + 1] = (lane_o == i0 + 1 ? 1.f : 0.f) - sum[1] - rv[ip][1] * t0;
;         }
.Lfs_ent1:
	ds_read_b128 v[78:81], v14 offset:4480
	ds_read_b128 v[130:133], v14 offset:5024
	s_waitcnt lgkmcnt(1)
	v_pk_fma_f32 v[62:63], v[78:79], v[8:9], 0 op_sel_hi:[1,0,0]
	v_pk_fma_f32 v[62:63], v[80:81], v[8:9], v[62:63] op_sel:[0,1,0] op_sel_hi:[1,1,1]
	s_nop 1
	v_add_f32_dpp v62, v62, v62 quad_perm:[1,0,3,2] row_mask:0xf bank_mask:0xf bound_ctrl:1
	v_add_f32_dpp v63, v63, v63 quad_perm:[1,0,3,2] row_mask:0xf bank_mask:0xf bound_ctrl:1
	s_nop 0
	v_add_f32_dpp v62, v62, v62 quad_perm:[2,3,0,1] row_mask:0xf bank_mask:0xf bound_ctrl:1
	v_add_f32_dpp v63, v63, v63 quad_perm:[2,3,0,1] row_mask:0xf bank_mask:0xf bound_ctrl:1
	s_mov_b64 exec, s[4:5]
	v_pk_add_f32 v[8:9], v[8:9], v[62:63] neg_lo:[0,1] neg_hi:[0,1]
	v_fma_f32 v9, v79, v62, v9
	s_mov_b64 exec, -1
	ds_read_b128 v[78:81], v14 offset:5568
	s_waitcnt lgkmcnt(1)
	v_pk_fma_f32 v[62:63], v[130:131], v[8:9], 0 op_sel_hi:[1,0,0]
	v_pk_fma_f32 v[62:63], v[132:133], v[8:9], v[62:63] op_sel:[0,1,0] op_sel_hi:[1,1,1]
	s_nop 1
	v_add_f32_dpp v62, v62, v62 quad_perm:[1,0,3,2] row_mask:0xf bank_mask:0xf bound_ctrl:1
	v_add_f32_dpp v63, v63, v63 quad_perm:[1,0,3,2] row_mask:0xf bank_mask:0xf bound_ctrl:1
	s_nop 0
	v_add_f32_dpp v62, v62, v62 quad_perm:[2,3,0,1] row_mask:0xf bank_mask:0xf bound_ctrl:1
	v_add_f32_dpp v63, v63, v63 quad_perm:[2,3,0,1] row_mask:0xf bank_mask:0xf bound_ctrl:1
	s_mov_b64 exec, s[6:7]
	v_pk_add_f32 v[8:9], v[8:9], v[62:63] neg_lo:[0,1] neg_hi:[0,1]
	v_fma_f32 v9, v131, v62, v9
	s_mov_b64 exec, -1
	ds_read_b128 v[130:133], v14 offset:6112
	s_waitcnt lgkmcnt(1)
	v_pk_fma_f32 v[62:63], v[78:79], v[8:9], 0 op_sel_hi:[1,0,0]
	v_pk_fma_f32 v[62:63], v[80:81], v[8:9], v[62:63] op_sel:[0,1,0] op_sel_hi:[1,1,1]
	s_nop 1
	v_add_f32_dpp v62, v62, v62 quad_perm:[1,0,3,2] row_mask:0xf bank_mask:0xf bound_ctrl:1
	v_add_f32_dpp v63, v63, v63 quad_perm:[1,0,3,2] row_mask:0xf bank_mask:0xf bound_ctrl:1
	s_nop 0
	v_add_f32_dpp v62, v62, v62 quad_perm:[2,3,0,1] row_mask:0xf bank_mask:0xf bound_ctrl:1
	v_add_f32_dpp v63, v63, v63 quad_perm:[2,3,0,1] row_mask:0xf bank_mask:0xf bound_ctrl:1
	s_mov_b64 exec, s[8:9]
	v_pk_add_f32 v[8:9], v[8:9], v[62:63] neg_lo:[0,1] neg_hi:[0,1]
	v_fma_f32 v9, v79, v62, v9
	s_mov_b64 exec, -1
	ds_read_b128 v[78:81], v14 offset:6656
	ds_read_b128 v[82:85], v14 offset:6720
	s_waitcnt lgkmcnt(2)
	v_pk_fma_f32 v[62:63], v[130:131], v[8:9], 0 op_sel_hi:[1,0,0]
	v_pk_fma_f32 v[62:63], v[132:133], v[8:9], v[62:63] op_sel:[0,1,0] op_sel_hi:[1,1,1]
	s_nop 1
	v_add_f32_dpp v62, v62, v62 quad_perm:[1,0,3,2] row_mask:0xf bank_mask:0xf bound_ctrl:1
	v_add_f32_dpp v63, v63, v63 quad_perm:[1,0,3,2] row_mask:0xf bank_mask:0xf bound_ctrl:1
	s_nop 0
	v_add_f32_dpp v62, v62, v62 quad_perm:[2,3,0,1] row_mask:0xf bank_mask:0xf bound_ctrl:1
	v_add_f32_dpp v63, v63, v63 quad_perm:[2,3,0,1] row_mask:0xf bank_mask:0xf bound_ctrl:1
	s_mov_b64 exec, s[10:11]
	v_pk_add_f32 v[8:9], v[8:9], v[62:63] neg_lo:[0,1] neg_hi:[0,1]
	v_fma_f32 v9, v131, v62, v9
	s_mov_b64 exec, -1
	ds_read_b128 v[130:133], v14 offset:7200
	ds_read_b128 v[38:41], v14 offset:7264
	s_waitcnt lgkmcnt(2)
	v_pk_fma_f32 v[62:63], v[82:83], v[10:11], 0 op_sel_hi:[1,0,0]
	v_pk_fma_f32 v[62:63], v[84:85], v[10:11], v[62:63] op_sel:[0,1,0] op_sel_hi:[1,1,1]
	v_pk_fma_f32 v[62:63], v[78:79], v[8:9], v[62:63] op_sel_hi:[1,0,1]
	v_pk_fma_f32 v[62:63], v[80:81], v[8:9], v[62:63] op_sel:[0,1,0] op_sel_hi:[1,1,1]
	s_nop 1
	v_add_f32_dpp v62, v62, v62 quad_perm:[1,0,3,2] row_mask:0xf bank_mask:0xf bound_ctrl:1
	v_add_f32_dpp v63, v63, v63 quad_perm:[1,0,3,2] row_mask:0xf bank_mask:0xf bound_ctrl:1
	s_nop 0
	v_add_f32_dpp v62, v62, v62 quad_perm:[2,3,0,1] row_mask:0xf bank_mask:0xf bound_ctrl:1
	v_add_f32_dpp v63, v63, v63 quad_perm:[2,3,0,1] row_mask:0xf bank_mask:0xf bound_ctrl:1
	s_mov_b64 exec, s[4:5]
	v_pk_add_f32 v[10:11], v[10:11], v[62:63] neg_lo:[0,1] neg_hi:[0,1]
	v_fma_f32 v11, v83, v62, v11
	s_mov_b64 exec, -1
	ds_read_b128 v[78:81], v14 offset:7744
	ds_read_b128 v[82:85], v14 offset:7808
	s_waitcnt lgkmcnt(2)
	v_pk_fma_f32 v[62:63], v[130:131], v[8:9], 0 op_sel_hi:[1,0,0]
	v_pk_fma_f32 v[62:63], v[132:133], v[8:9], v[62:63] op_sel:[0,1,0] op_sel_hi:[1,1,1]
	v_pk_fma_f32 v[62:63], v[38:39], v[10:11], v[62:63] op_sel_hi:[1,0,1]
	v_pk_fma_f32 v[62:63], v[40:41], v[10:11], v[62:63] op_sel:[0,1,0] op_sel_hi:[1,1,1]
	s_nop 1
	v_add_f32_dpp v62, v62, v62 quad_perm:[1,0,3,2] row_mask:0xf bank_mask:0xf bound_ctrl:1
	v_add_f32_dpp v63, v63, v63 quad_perm:[1,0,3,2] row_mask:0xf bank_mask:0xf bound_ctrl:1
	s_nop 0
	v_add_f32_dpp v62, v62, v62 quad_perm:[2,3,0,1] row_mask:0xf bank_mask:0xf bound_ctrl:1
	v_add_f32_dpp v63, v63, v63 quad_perm:[2,3,0,1] row_mask:0xf bank_mask:0xf bound_ctrl:1
	s_mov_b64 exec, s[6:7]
	v_pk_add_f32 v[10:11], v[10:11], v[62:63] neg_lo:[0,1] neg_hi:[0,1]
	v_fma_f32 v11, v39, v62, v11
	s_mov_b64 exec, -1
	ds_read_b128 v[130:133], v14 offset:8288
	ds_read_b128 v[38:41], v14 offset:8352
	s_waitcnt lgkmcnt(2)
	v_pk_fma_f32 v[62:63], v[78:79], v[8:9], 0 op_sel_hi:[1,0,0]
	v_pk_fma_f32 v[62:63], v[80:81], v[8:9], v[62:63] op_sel:[0,1,0] op_sel_hi:[1,1,1]
	v_pk_fma_f32 v[62:63], v[82:83], v[10:11], v[62:63] op_sel_hi:[1,0,1]
	v_pk_fma_f32 v[62:63], v[84:85], v[10:11], v[62:63] op_sel:[0,1,0] op_sel_hi:[1,1,1]
	s_nop 1
	v_add_f32_dpp v62, v62, v62 quad_perm:[1,0,3,2] row_mask:0xf bank_mask:0xf bound_ctrl:1
	v_add_f32_dpp v63, v63, v63 quad_perm:[1,0,3,2] row_mask:0xf bank_mask:0xf bound_ctrl:1
	s_nop 0
	v_add_f32_dpp v62, v62, v62 quad_perm:[2,3,0,1] row_mask:0xf bank_mask:0xf bound_ctrl:1
	v_add_f32_dpp v63, v63, v63 quad_perm:[2,3,0,1] row_mask:0xf bank_mask:0xf bound_ctrl:1
	s_mov_b64 exec, s[8:9]
	v_pk_add_f32 v[10:11], v[10:11], v[62:63] neg_lo:[0,1] neg_hi:[0,1]
	v_fma_f32 v11, v83, v62, v11
	s_mov_b64 exec, -1
	ds_read_b128 v[78:81], v14 offset:8832
	ds_read_b128 v[82:85], v14 offset:8896
	ds_read_b128 v[86:89], v14 offset:8960
	s_waitcnt lgkmcnt(3)
; #define LAS __attribute__((address_space(3)))
;     ...
;     if (w < 2) {
;         const int d = w; const LAS float* Ad = As + d * 4352;
;         float tr[64]; int lane_o = lane;
; #pragma unroll
;         for (int ip = 0; ip < 32; ++ip) {
;             const int i0 = 2 * ip;
;             f32x4 rv[32];
; #pragma unroll
;             for (int jp = 0; jp <= ip; ++jp) rv[jp] = *(const LAS f32x4*)(Ad + ip * 136 + 4 * jp);
;             asm volatile("" : "+v"(lane_o) :: "memory");
;             f32x2_ a0 = {0.f, 0.f}, a1 = {0.f, 0.f}, a2 = {0.f, 0.f}, a3 = {0.f, 0.f};
; #pragma unroll
;             for (int jp = 0; jp < ip; ++jp) {
;                 const f32x2_ ta = {tr[2 * jp], tr[2 * jp]}, tb = {tr[2 * jp + 1], tr[2 * jp + 1]};
;                 const f32x2_ va = {rv[jp][0], rv[jp][1]}, vb = {rv[jp][2], rv[jp][3]};
;                 if (jp & 1) { a2 += va * ta; a3 += vb * tb; } else { a0 += va * ta; a1 += vb * tb; }
;             }
;             const f32x2_ sum = (a0 + a1) + (a2 + a3);
;             const float t0 = (lane_o == i0 ? 1.f : 0.f) - sum[0];
;             tr[i0] = t0;
;             tr[i0 + 1] = (lane_o == i0 + 1 ? 1.f : 0.f) - sum[1] - rv[ip][1] * t0;
;         }
	v_pk_fma_f32 v[62:63], v[130:131], v[8:9], 0 op_sel_hi:[1,0,0]
	v_pk_fma_f32 v[62:63], v[132:133], v[8:9], v[62:63] op_sel:[0,1,0] op_sel_hi:[1,1,1]
	v_pk_fma_f32 v[62:63], v[38:39], v[10:11], v[62:63] op_sel_hi:[1,0,1]
	v_pk_fma_f32 v[62:63], v[40:41], v[10:11], v[62:63] op_sel:[0,1,0] op_sel_hi:[1,1,1]
	s_nop 1
	v_add_f32_dpp v62, v62, v62 quad_perm:[1,0,3,2] row_mask:0xf bank_mask:0xf bound_ctrl:1
	v_add_f32_dpp v63, v63, v63 quad_perm:[1,0,3,2] row_mask:0xf bank_mask:0xf bound_ctrl:1
	s_nop 0
	v_add_f32_dpp v62, v62, v62 quad_perm:[2,3,0,1] row_mask:0xf bank_mask:0xf bound_ctrl:1
	v_add_f32_dpp v63, v63, v63 quad_perm:[2,3,0,1] row_mask:0xf bank_mask:0xf bound_ctrl:1
	s_mov_b64 exec, s[10:11]
	v_pk_add_f32 v[10:11], v[10:11], v[62:63] neg_lo:[0,1] neg_hi:[0,1]
	v_fma_f32 v11, v39, v62, v11
	s_mov_b64 exec, -1
	ds_read_b128 v[130:133], v14 offset:9376
	ds_read_b128 v[38:41], v14 offset:9440
	ds_read_b128 v[42:45], v14 offset:9504
	s_waitcnt lgkmcnt(3)
	v_pk_fma_f32 v[62:63], v[78:79], v[8:9], 0 op_sel_hi:[1,0,0]
	v_pk_fma_f32 v[62:63], v[80:81], v[8:9], v[62:63] op_sel:[0,1,0] op_sel_hi:[1,1,1]
	v_pk_fma_f32 v[62:63], v[86:87], v[18:19], v[62:63] op_sel_hi:[1,0,1]
	v_pk_fma_f32 v[62:63], v[88:89], v[18:19], v[62:63] op_sel:[0,1,0] op_sel_hi:[1,1,1]
	v_pk_fma_f32 v[62:63], v[82:83], v[10:11], v[62:63] op_sel_hi:[1,0,1]
	v_pk_fma_f32 v[62:63], v[84:85], v[10:11], v[62:63] op_sel:[0,1,0] op_sel_hi:[1,1,1]
	s_nop 1
	v_add_f32_dpp v62, v62, v62 quad_perm:[1,0,3,2] row_mask:0xf bank_mask:0xf bound_ctrl:1
	v_add_f32_dpp v63, v63, v63 quad_perm:[1,0,3,2] row_mask:0xf bank_mask:0xf bound_ctrl:1
	s_nop 0
	v_add_f32_dpp v62, v62, v62 quad_perm:[2,3,0,1] row_mask:0xf bank_mask:0xf bound_ctrl:1
	v_add_f32_dpp v63, v63, v63 quad_perm:[2,3,0,1] row_mask:0xf bank_mask:0xf bound_ctrl:1
	s_mov_b64 exec, s[4:5]
	v_pk_add_f32 v[18:19], v[18:19], v[62:63] neg_lo:[0,1] neg_hi:[0,1]
	v_fma_f32 v19, v87, v62, v19
	s_mov_b64 exec, -1
	ds_read_b128 v[78:81], v14 offset:9920
	ds_read_b128 v[82:85], v14 offset:9984
	ds_read_b128 v[86:89], v14 offset:10048
	s_waitcnt lgkmcnt(3)
	v_pk_fma_f32 v[62:63], v[130:131], v[8:9], 0 op_sel_hi:[1,0,0]
	v_pk_fma_f32 v[62:63], v[132:133], v[8:9], v[62:63] op_sel:[0,1,0] op_sel_hi:[1,1,1]
	v_pk_fma_f32 v[62:63], v[38:39], v[10:11], v[62:63] op_sel_hi:[1,0,1]
	v_pk_fma_f32 v[62:63], v[40:41], v[10:11], v[62:63] op_sel:[0,1,0] op_sel_hi:[1,1,1]
	v_pk_fma_f32 v[62:63], v[42:43], v[18:19], v[62:63] op_sel_hi:[1,0,1]
	v_pk_fma_f32 v[62:63], v[44:45], v[18:19], v[62:63] op_sel:[0,1,0] op_sel_hi:[1,1,1]
	s_nop 1
	v_add_f32_dpp v62, v62, v62 quad_perm:[1,0,3,2] row_mask:0xf bank_mask:0xf bound_ctrl:1
	v_add_f32_dpp v63, v63, v63 quad_perm:[1,0,3,2] row_mask:0xf bank_mask:0xf bound_ctrl:1
	s_nop 0
	v_add_f32_dpp v62, v62, v62 quad_perm:[2,3,0,1] row_mask:0xf bank_mask:0xf bound_ctrl:1
	v_add_f32_dpp v63, v63, v63 quad_perm:[2,3,0,1] row_mask:0xf bank_mask:0xf bound_ctrl:1
	s_mov_b64 exec, s[6:7]
	v_pk_add_f32 v[18:19], v[18:19], v[62:63] neg_lo:[0,1] neg_hi:[0,1]
	v_fma_f32 v19, v43, v62, v19
	s_mov_b64 exec, -1
	ds_read_b128 v[130:133], v14 offset:10464
	ds_read_b128 v[38:41], v14 offset:10528
	ds_read_b128 v[42:45], v14 offset:10592
	s_waitcnt lgkmcnt(3)
	v_pk_fma_f32 v[62:63], v[78:79], v[8:9], 0 op_sel_hi:[1,0,0]
	v_pk_fma_f32 v[62:63], v[80:81], v[8:9], v[62:63] op_sel:[0,1,0] op_sel_hi:[1,1,1]
	v_pk_fma_f32 v[62:63], v[82:83], v[10:11], v[62:63] op_sel_hi:[1,0,1]
	v_pk_fma_f32 v[62:63], v[84:85], v[10:11], v[62:63] op_sel:[0,1,0] op_sel_hi:[1,1,1]
	v_pk_fma_f32 v[62:63], v[86:87], v[18:19], v[62:63] op_sel_hi:[1,0,1]
	v_pk_fma_f32 v[62:63], v[88:89], v[18:19], v[62:63] op_sel:[0,1,0] op_sel_hi:[1,1,1]
	s_nop 1
	v_add_f32_dpp v62, v62, v62 quad_perm:[1,0,3,2] row_mask:0xf bank_mask:0xf bound_ctrl:1
	v_add_f32_dpp v63, v63, v63 quad_perm:[1,0,3,2] row_mask:0xf bank_mask:0xf bound_ctrl:1
	s_nop 0
	v_add_f32_dpp v62, v62, v62 quad_perm:[2,3,0,1] row_mask:0xf bank_mask:0xf bound_ctrl:1
	v_add_f32_dpp v63, v63, v63 quad_perm:[2,3,0,1] row_mask:0xf bank_mask:0xf bound_ctrl:1
	s_mov_b64 exec, s[8:9]
	v_pk_add_f32 v[18:19], v[18:19], v[62:63] neg_lo:[0,1] neg_hi:[0,1]
	v_fma_f32 v19, v87, v62, v19
	s_mov_b64 exec, -1
	ds_read_b128 v[78:81], v14 offset:11008
	ds_read_b128 v[82:85], v14 offset:11072
	ds_read_b128 v[86:89], v14 offset:11136
	ds_read_b128 v[90:93], v14 offset:11200
	s_waitcnt lgkmcnt(4)
	v_pk_fma_f32 v[62:63], v[130:131], v[8:9], 0 op_sel_hi:[1,0,0]
	v_pk_fma_f32 v[62:63], v[132:133], v[8:9], v[62:63] op_sel:[0,1,0] op_sel_hi:[1,1,1]
	v_pk_fma_f32 v[62:63], v[38:39], v[10:11], v[62:63] op_sel_hi:[1,0,1]
	v_pk_fma_f32 v[62:63], v[40:41], v[10:11], v[62:63] op_sel:[0,1,0] op_sel_hi:[1,1,1]
	v_pk_fma_f32 v[62:63], v[42:43], v[18:19], v[62:63] op_sel_hi:[1,0,1]
	v_pk_fma_f32 v[62:63], v[44:45], v[18:19], v[62:63] op_sel:[0,1,0] op_sel_hi:[1,1,1]
	s_nop 1
	v_add_f32_dpp v62, v62, v62 quad_perm:[1,0,3,2] row_mask:0xf bank_mask:0xf bound_ctrl:1
	v_add_f32_dpp v63, v63, v63 quad_perm:[1,0,3,2] row_mask:0xf bank_mask:0xf bound_ctrl:1
	s_nop 0
	v_add_f32_dpp v62, v62, v62 quad_perm:[2,3,0,1] row_mask:0xf bank_mask:0xf bound_ctrl:1
	v_add_f32_dpp v63, v63, v63 quad_perm:[2,3,0,1] row_mask:0xf bank_mask:0xf bound_ctrl:1
	s_mov_b64 exec, s[10:11]
	v_pk_add_f32 v[18:19], v[18:19], v[62:63] neg_lo:[0,1] neg_hi:[0,1]
	v_fma_f32 v19, v43, v62, v19
	s_mov_b64 exec, -1
	ds_read_b128 v[130:133], v14 offset:11552
	ds_read_b128 v[38:41], v14 offset:11616
	ds_read_b128 v[42:45], v14 offset:11680
	ds_read_b128 v[46:49], v14 offset:11744
	s_waitcnt lgkmcnt(4)
; #define LAS __attribute__((address_space(3)))
;     ...
;     if (w < 2) {
;         const int d = w; const LAS float* Ad = As + d * 4352;
;         float tr[64]; int lane_o = lane;
; #pragma unroll
;         for (int ip = 0; ip < 32; ++ip) {
;             const int i0 = 2 * ip;
;             f32x4 rv[32];
; #pragma unroll
;             for (int jp = 0; jp <= ip; ++jp) rv[jp] = *(const LAS f32x4*)(Ad + ip * 136 + 4 * jp);
;             asm volatile("" : "+v"(lane_o) :: "memory");
;             f32x2_ a0 = {0.f, 0.f}, a1 = {0.f, 0.f}, a2 = {0.f, 0.f}, a3 = {0.f, 0.f};
; #pragma unroll
;             for (int jp = 0; jp < ip; ++jp) {
;                 const f32x2_ ta = {tr[2 * jp], tr[2 * jp]}, tb = {tr[2 * jp + 1], tr[2 * jp + 1]};
;                 const f32x2_ va = {rv[jp][0], rv[jp][1]}, vb = {rv[jp][2], rv[jp][3]};
;                 if (jp & 1) { a2 += va * ta; a3 += vb * tb; } else { a0 += va * ta; a1 += vb * tb; }
;             }
;             const f32x2_ sum = (a0 + a1) + (a2 + a3);
;             const float t0 = (lane_o == i0 ? 1.f : 0.f) - sum[0];
;             tr[i0] = t0;
;             tr[i0 + 1] = (lane_o == i0 + 1 ? 1.f : 0.f) - sum[1] - rv[ip][1] * t0;
;         }
	v_pk_fma_f32 v[62:63], v[78:79], v[8:9], 0 op_sel_hi:[1,0,0]
	v_pk_fma_f32 v[62:63], v[80:81], v[8:9], v[62:63] op_sel:[0,1,0] op_sel_hi:[1,1,1]
	v_pk_fma_f32 v[62:63], v[82:83], v[10:11], v[62:63] op_sel_hi:[1,0,1]
	v_pk_fma_f32 v[62:63], v[84:85], v[10:11], v[62:63] op_sel:[0,1,0] op_sel_hi:[1,1,1]
	v_pk_fma_f32 v[62:63], v[90:91], v[50:51], v[62:63] op_sel_hi:[1,0,1]
	v_pk_fma_f32 v[62:63], v[92:93], v[50:51], v[62:63] op_sel:[0,1,0] op_sel_hi:[1,1,1]
	v_pk_fma_f32 v[62:63], v[86:87], v[18:19], v[62:63] op_sel_hi:[1,0,1]
	v_pk_fma_f32 v[62:63], v[88:89], v[18:19], v[62:63] op_sel:[0,1,0] op_sel_hi:[1,1,1]
	s_nop 1
	v_add_f32_dpp v62, v62, v62 quad_perm:[1,0,3,2] row_mask:0xf bank_mask:0xf bound_ctrl:1
	v_add_f32_dpp v63, v63, v63 quad_perm:[1,0,3,2] row_mask:0xf bank_mask:0xf bound_ctrl:1
	s_nop 0
	v_add_f32_dpp v62, v62, v62 quad_perm:[2,3,0,1] row_mask:0xf bank_mask:0xf bound_ctrl:1
	v_add_f32_dpp v63, v63, v63 quad_perm:[2,3,0,1] row_mask:0xf bank_mask:0xf bound_ctrl:1
	s_mov_b64 exec, s[4:5]
	v_pk_add_f32 v[50:51], v[50:51], v[62:63] neg_lo:[0,1] neg_hi:[0,1]
	v_fma_f32 v51, v91, v62, v51
	s_mov_b64 exec, -1
	ds_read_b128 v[78:81], v14 offset:12096
	ds_read_b128 v[82:85], v14 offset:12160
	ds_read_b128 v[86:89], v14 offset:12224
	ds_read_b128 v[90:93], v14 offset:12288
	s_waitcnt lgkmcnt(4)
	v_pk_fma_f32 v[62:63], v[130:131], v[8:9], 0 op_sel_hi:[1,0,0]
	v_pk_fma_f32 v[62:63], v[132:133], v[8:9], v[62:63] op_sel:[0,1,0] op_sel_hi:[1,1,1]
	v_pk_fma_f32 v[62:63], v[38:39], v[10:11], v[62:63] op_sel_hi:[1,0,1]
	v_pk_fma_f32 v[62:63], v[40:41], v[10:11], v[62:63] op_sel:[0,1,0] op_sel_hi:[1,1,1]
	v_pk_fma_f32 v[62:63], v[42:43], v[18:19], v[62:63] op_sel_hi:[1,0,1]
	v_pk_fma_f32 v[62:63], v[44:45], v[18:19], v[62:63] op_sel:[0,1,0] op_sel_hi:[1,1,1]
	v_pk_fma_f32 v[62:63], v[46:47], v[50:51], v[62:63] op_sel_hi:[1,0,1]
	v_pk_fma_f32 v[62:63], v[48:49], v[50:51], v[62:63] op_sel:[0,1,0] op_sel_hi:[1,1,1]
	s_nop 1
	v_add_f32_dpp v62, v62, v62 quad_perm:[1,0,3,2] row_mask:0xf bank_mask:0xf bound_ctrl:1
	v_add_f32_dpp v63, v63, v63 quad_perm:[1,0,3,2] row_mask:0xf bank_mask:0xf bound_ctrl:1
	s_nop 0
	v_add_f32_dpp v62, v62, v62 quad_perm:[2,3,0,1] row_mask:0xf bank_mask:0xf bound_ctrl:1
	v_add_f32_dpp v63, v63, v63 quad_perm:[2,3,0,1] row_mask:0xf bank_mask:0xf bound_ctrl:1
	s_mov_b64 exec, s[6:7]
	v_pk_add_f32 v[50:51], v[50:51], v[62:63] neg_lo:[0,1] neg_hi:[0,1]
	v_fma_f32 v51, v47, v62, v51
	s_mov_b64 exec, -1
	ds_read_b128 v[130:133], v14 offset:12640
	ds_read_b128 v[38:41], v14 offset:12704
	ds_read_b128 v[42:45], v14 offset:12768
	ds_read_b128 v[46:49], v14 offset:12832
	s_waitcnt lgkmcnt(4)
	v_pk_fma_f32 v[62:63], v[78:79], v[8:9], 0 op_sel_hi:[1,0,0]
	v_pk_fma_f32 v[62:63], v[80:81], v[8:9], v[62:63] op_sel:[0,1,0] op_sel_hi:[1,1,1]
	v_pk_fma_f32 v[62:63], v[82:83], v[10:11], v[62:63] op_sel_hi:[1,0,1]
	v_pk_fma_f32 v[62:63], v[84:85], v[10:11], v[62:63] op_sel:[0,1,0] op_sel_hi:[1,1,1]
	v_pk_fma_f32 v[62:63], v[86:87], v[18:19], v[62:63] op_sel_hi:[1,0,1]
	v_pk_fma_f32 v[62:63], v[88:89], v[18:19], v[62:63] op_sel:[0,1,0] op_sel_hi:[1,1,1]
	v_pk_fma_f32 v[62:63], v[90:91], v[50:51], v[62:63] op_sel_hi:[1,0,1]
	v_pk_fma_f32 v[62:63], v[92:93], v[50:51], v[62:63] op_sel:[0,1,0] op_sel_hi:[1,1,1]
	s_nop 1
	v_add_f32_dpp v62, v62, v62 quad_perm:[1,0,3,2] row_mask:0xf bank_mask:0xf bound_ctrl:1
	v_add_f32_dpp v63, v63, v63 quad_perm:[1,0,3,2] row_mask:0xf bank_mask:0xf bound_ctrl:1
	s_nop 0
	v_add_f32_dpp v62, v62, v62 quad_perm:[2,3,0,1] row_mask:0xf bank_mask:0xf bound_ctrl:1
	v_add_f32_dpp v63, v63, v63 quad_perm:[2,3,0,1] row_mask:0xf bank_mask:0xf bound_ctrl:1
	s_mov_b64 exec, s[8:9]
	v_pk_add_f32 v[50:51], v[50:51], v[62:63] neg_lo:[0,1] neg_hi:[0,1]
	v_fma_f32 v51, v91, v62, v51
	s_mov_b64 exec, -1
	ds_read_b128 v[78:81], v14 offset:13184
	ds_read_b128 v[82:85], v14 offset:13248
	ds_read_b128 v[86:89], v14 offset:13312
	ds_read_b128 v[90:93], v14 offset:13376
	ds_read_b128 v[94:97], v14 offset:13440
	s_waitcnt lgkmcnt(5)
	v_pk_fma_f32 v[62:63], v[130:131], v[8:9], 0 op_sel_hi:[1,0,0]
	v_pk_fma_f32 v[62:63], v[132:133], v[8:9], v[62:63] op_sel:[0,1,0] op_sel_hi:[1,1,1]
	v_pk_fma_f32 v[62:63], v[38:39], v[10:11], v[62:63] op_sel_hi:[1,0,1]
	v_pk_fma_f32 v[62:63], v[40:41], v[10:11], v[62:63] op_sel:[0,1,0] op_sel_hi:[1,1,1]
	v_pk_fma_f32 v[62:63], v[42:43], v[18:19], v[62:63] op_sel_hi:[1,0,1]
	v_pk_fma_f32 v[62:63], v[44:45], v[18:19], v[62:63] op_sel:[0,1,0] op_sel_hi:[1,1,1]
	v_pk_fma_f32 v[62:63], v[46:47], v[50:51], v[62:63] op_sel_hi:[1,0,1]
	v_pk_fma_f32 v[62:63], v[48:49], v[50:51], v[62:63] op_sel:[0,1,0] op_sel_hi:[1,1,1]
	s_nop 1
	v_add_f32_dpp v62, v62, v62 quad_perm:[1,0,3,2] row_mask:0xf bank_mask:0xf bound_ctrl:1
	v_add_f32_dpp v63, v63, v63 quad_perm:[1,0,3,2] row_mask:0xf bank_mask:0xf bound_ctrl:1
	s_nop 0
	v_add_f32_dpp v62, v62, v62 quad_perm:[2,3,0,1] row_mask:0xf bank_mask:0xf bound_ctrl:1
	v_add_f32_dpp v63, v63, v63 quad_perm:[2,3,0,1] row_mask:0xf bank_mask:0xf bound_ctrl:1
	s_mov_b64 exec, s[10:11]
	v_pk_add_f32 v[50:51], v[50:51], v[62:63] neg_lo:[0,1] neg_hi:[0,1]
	v_fma_f32 v51, v47, v62, v51
	s_mov_b64 exec, -1
	ds_read_b128 v[130:133], v14 offset:13728
	ds_read_b128 v[38:41], v14 offset:13792
	ds_read_b128 v[42:45], v14 offset:13856
	ds_read_b128 v[46:49], v14 offset:13920
	ds_read_b128 v[102:105], v14 offset:13984
	s_waitcnt lgkmcnt(5)
; #define LAS __attribute__((address_space(3)))
;     ...
;     if (w < 2) {
;         const int d = w; const LAS float* Ad = As + d * 4352;
;         float tr[64]; int lane_o = lane;
; #pragma unroll
;         for (int ip = 0; ip < 32; ++ip) {
;             const int i0 = 2 * ip;
;             f32x4 rv[32];
; #pragma unroll
;             for (int jp = 0; jp <= ip; ++jp) rv[jp] = *(const LAS f32x4*)(Ad + ip * 136 + 4 * jp);
;             asm volatile("" : "+v"(lane_o) :: "memory");
;             f32x2_ a0 = {0.f, 0.f}, a1 = {0.f, 0.f}, a2 = {0.f, 0.f}, a3 = {0.f, 0.f};
; #pragma unroll
;             for (int jp = 0; jp < ip; ++jp) {
;                 const f32x2_ ta = {tr[2 * jp], tr[2 * jp]}, tb = {tr[2 * jp + 1], tr[2 * jp + 1]};
;                 const f32x2_ va = {rv[jp][0], rv[jp][1]}, vb = {rv[jp][2], rv[jp][3]};
;                 if (jp & 1) { a2 += va * ta; a3 += vb * tb; } else { a0 += va * ta; a1 += vb * tb; }
;             }
;             const f32x2_ sum = (a0 + a1) + (a2 + a3);
;             const float t0 = (lane_o == i0 ? 1.f : 0.f) - sum[0];
;             tr[i0] = t0;
;             tr[i0 + 1] = (lane_o == i0 + 1 ? 1.f : 0.f) - sum[1] - rv[ip][1] * t0;
;         }
	v_pk_fma_f32 v[62:63], v[78:79], v[8:9], 0 op_sel_hi:[1,0,0]
	v_pk_fma_f32 v[62:63], v[80:81], v[8:9], v[62:63] op_sel:[0,1,0] op_sel_hi:[1,1,1]
	v_pk_fma_f32 v[62:63], v[82:83], v[10:11], v[62:63] op_sel_hi:[1,0,1]
	v_pk_fma_f32 v[62:63], v[84:85], v[10:11], v[62:63] op_sel:[0,1,0] op_sel_hi:[1,1,1]
	v_pk_fma_f32 v[62:63], v[86:87], v[18:19], v[62:63] op_sel_hi:[1,0,1]
	v_pk_fma_f32 v[62:63], v[88:89], v[18:19], v[62:63] op_sel:[0,1,0] op_sel_hi:[1,1,1]
	v_pk_fma_f32 v[62:63], v[94:95], v[54:55], v[62:63] op_sel_hi:[1,0,1]
	v_pk_fma_f32 v[62:63], v[96:97], v[54:55], v[62:63] op_sel:[0,1,0] op_sel_hi:[1,1,1]
	v_pk_fma_f32 v[62:63], v[90:91], v[50:51], v[62:63] op_sel_hi:[1,0,1]
	v_pk_fma_f32 v[62:63], v[92:93], v[50:51], v[62:63] op_sel:[0,1,0] op_sel_hi:[1,1,1]
	s_nop 1
	v_add_f32_dpp v62, v62, v62 quad_perm:[1,0,3,2] row_mask:0xf bank_mask:0xf bound_ctrl:1
	v_add_f32_dpp v63, v63, v63 quad_perm:[1,0,3,2] row_mask:0xf bank_mask:0xf bound_ctrl:1
	s_nop 0
	v_add_f32_dpp v62, v62, v62 quad_perm:[2,3,0,1] row_mask:0xf bank_mask:0xf bound_ctrl:1
	v_add_f32_dpp v63, v63, v63 quad_perm:[2,3,0,1] row_mask:0xf bank_mask:0xf bound_ctrl:1
	s_mov_b64 exec, s[4:5]
	v_pk_add_f32 v[54:55], v[54:55], v[62:63] neg_lo:[0,1] neg_hi:[0,1]
	v_fma_f32 v55, v95, v62, v55
	s_mov_b64 exec, -1
	ds_read_b128 v[78:81], v14 offset:14272
	ds_read_b128 v[82:85], v14 offset:14336
	ds_read_b128 v[86:89], v14 offset:14400
	ds_read_b128 v[90:93], v14 offset:14464
	ds_read_b128 v[94:97], v14 offset:14528
	s_waitcnt lgkmcnt(5)
	v_pk_fma_f32 v[62:63], v[130:131], v[8:9], 0 op_sel_hi:[1,0,0]
	v_pk_fma_f32 v[62:63], v[132:133], v[8:9], v[62:63] op_sel:[0,1,0] op_sel_hi:[1,1,1]
	v_pk_fma_f32 v[62:63], v[38:39], v[10:11], v[62:63] op_sel_hi:[1,0,1]
	v_pk_fma_f32 v[62:63], v[40:41], v[10:11], v[62:63] op_sel:[0,1,0] op_sel_hi:[1,1,1]
	v_pk_fma_f32 v[62:63], v[42:43], v[18:19], v[62:63] op_sel_hi:[1,0,1]
	v_pk_fma_f32 v[62:63], v[44:45], v[18:19], v[62:63] op_sel:[0,1,0] op_sel_hi:[1,1,1]
	v_pk_fma_f32 v[62:63], v[46:47], v[50:51], v[62:63] op_sel_hi:[1,0,1]
	v_pk_fma_f32 v[62:63], v[48:49], v[50:51], v[62:63] op_sel:[0,1,0] op_sel_hi:[1,1,1]
	v_pk_fma_f32 v[62:63], v[102:103], v[54:55], v[62:63] op_sel_hi:[1,0,1]
	v_pk_fma_f32 v[62:63], v[104:105], v[54:55], v[62:63] op_sel:[0,1,0] op_sel_hi:[1,1,1]
	s_nop 1
	v_add_f32_dpp v62, v62, v62 quad_perm:[1,0,3,2] row_mask:0xf bank_mask:0xf bound_ctrl:1
	v_add_f32_dpp v63, v63, v63 quad_perm:[1,0,3,2] row_mask:0xf bank_mask:0xf bound_ctrl:1
	s_nop 0
	v_add_f32_dpp v62, v62, v62 quad_perm:[2,3,0,1] row_mask:0xf bank_mask:0xf bound_ctrl:1
	v_add_f32_dpp v63, v63, v63 quad_perm:[2,3,0,1] row_mask:0xf bank_mask:0xf bound_ctrl:1
	s_mov_b64 exec, s[6:7]
	v_pk_add_f32 v[54:55], v[54:55], v[62:63] neg_lo:[0,1] neg_hi:[0,1]
	v_fma_f32 v55, v103, v62, v55
	s_mov_b64 exec, -1
	ds_read_b128 v[130:133], v14 offset:14816
	ds_read_b128 v[38:41], v14 offset:14880
	ds_read_b128 v[42:45], v14 offset:14944
	ds_read_b128 v[46:49], v14 offset:15008
	ds_read_b128 v[102:105], v14 offset:15072
	s_waitcnt lgkmcnt(5)
	v_pk_fma_f32 v[62:63], v[78:79], v[8:9], 0 op_sel_hi:[1,0,0]
	v_pk_fma_f32 v[62:63], v[80:81], v[8:9], v[62:63] op_sel:[0,1,0] op_sel_hi:[1,1,1]
	v_pk_fma_f32 v[62:63], v[82:83], v[10:11], v[62:63] op_sel_hi:[1,0,1]
	v_pk_fma_f32 v[62:63], v[84:85], v[10:11], v[62:63] op_sel:[0,1,0] op_sel_hi:[1,1,1]
	v_pk_fma_f32 v[62:63], v[86:87], v[18:19], v[62:63] op_sel_hi:[1,0,1]
	v_pk_fma_f32 v[62:63], v[88:89], v[18:19], v[62:63] op_sel:[0,1,0] op_sel_hi:[1,1,1]
	v_pk_fma_f32 v[62:63], v[90:91], v[50:51], v[62:63] op_sel_hi:[1,0,1]
	v_pk_fma_f32 v[62:63], v[92:93], v[50:51], v[62:63] op_sel:[0,1,0] op_sel_hi:[1,1,1]
	v_pk_fma_f32 v[62:63], v[94:95], v[54:55], v[62:63] op_sel_hi:[1,0,1]
	v_pk_fma_f32 v[62:63], v[96:97], v[54:55], v[62:63] op_sel:[0,1,0] op_sel_hi:[1,1,1]
	s_nop 1
	v_add_f32_dpp v62, v62, v62 quad_perm:[1,0,3,2] row_mask:0xf bank_mask:0xf bound_ctrl:1
	v_add_f32_dpp v63, v63, v63 quad_perm:[1,0,3,2] row_mask:0xf bank_mask:0xf bound_ctrl:1
	s_nop 0
	v_add_f32_dpp v62, v62, v62 quad_perm:[2,3,0,1] row_mask:0xf bank_mask:0xf bound_ctrl:1
	v_add_f32_dpp v63, v63, v63 quad_perm:[2,3,0,1] row_mask:0xf bank_mask:0xf bound_ctrl:1
	s_mov_b64 exec, s[8:9]
	v_pk_add_f32 v[54:55], v[54:55], v[62:63] neg_lo:[0,1] neg_hi:[0,1]
	v_fma_f32 v55, v95, v62, v55
	s_mov_b64 exec, -1
	ds_read_b128 v[78:81], v14 offset:15360
	ds_read_b128 v[82:85], v14 offset:15424
	ds_read_b128 v[86:89], v14 offset:15488
	ds_read_b128 v[90:93], v14 offset:15552
	ds_read_b128 v[94:97], v14 offset:15616
	ds_read_b128 v[98:101], v14 offset:15680
	s_waitcnt lgkmcnt(6)
	v_pk_fma_f32 v[62:63], v[130:131], v[8:9], 0 op_sel_hi:[1,0,0]
	v_pk_fma_f32 v[62:63], v[132:133], v[8:9], v[62:63] op_sel:[0,1,0] op_sel_hi:[1,1,1]
	v_pk_fma_f32 v[62:63], v[38:39], v[10:11], v[62:63] op_sel_hi:[1,0,1]
	v_pk_fma_f32 v[62:63], v[40:41], v[10:11], v[62:63] op_sel:[0,1,0] op_sel_hi:[1,1,1]
	v_pk_fma_f32 v[62:63], v[42:43], v[18:19], v[62:63] op_sel_hi:[1,0,1]
	v_pk_fma_f32 v[62:63], v[44:45], v[18:19], v[62:63] op_sel:[0,1,0] op_sel_hi:[1,1,1]
	v_pk_fma_f32 v[62:63], v[46:47], v[50:51], v[62:63] op_sel_hi:[1,0,1]
	v_pk_fma_f32 v[62:63], v[48:49], v[50:51], v[62:63] op_sel:[0,1,0] op_sel_hi:[1,1,1]
	v_pk_fma_f32 v[62:63], v[102:103], v[54:55], v[62:63] op_sel_hi:[1,0,1]
	v_pk_fma_f32 v[62:63], v[104:105], v[54:55], v[62:63] op_sel:[0,1,0] op_sel_hi:[1,1,1]
	s_nop 1
	v_add_f32_dpp v62, v62, v62 quad_perm:[1,0,3,2] row_mask:0xf bank_mask:0xf bound_ctrl:1
	v_add_f32_dpp v63, v63, v63 quad_perm:[1,0,3,2] row_mask:0xf bank_mask:0xf bound_ctrl:1
	s_nop 0
	v_add_f32_dpp v62, v62, v62 quad_perm:[2,3,0,1] row_mask:0xf bank_mask:0xf bound_ctrl:1
	v_add_f32_dpp v63, v63, v63 quad_perm:[2,3,0,1] row_mask:0xf bank_mask:0xf bound_ctrl:1
	s_mov_b64 exec, s[10:11]
	v_pk_add_f32 v[54:55], v[54:55], v[62:63] neg_lo:[0,1] neg_hi:[0,1]
	v_fma_f32 v55, v103, v62, v55
	s_mov_b64 exec, -1
	ds_read_b128 v[130:133], v14 offset:15904
	ds_read_b128 v[38:41], v14 offset:15968
	ds_read_b128 v[42:45], v14 offset:16032
	ds_read_b128 v[46:49], v14 offset:16096
	ds_read_b128 v[102:105], v14 offset:16160
	ds_read_b128 v[242:245], v14 offset:16224
	s_waitcnt lgkmcnt(6)
; #define LAS __attribute__((address_space(3)))
;     ...
;     if (w < 2) {
;         const int d = w; const LAS float* Ad = As + d * 4352;
;         float tr[64]; int lane_o = lane;
; #pragma unroll
;         for (int ip = 0; ip < 32; ++ip) {
;             const int i0 = 2 * ip;
;             f32x4 rv[32];
; #pragma unroll
;             for (int jp = 0; jp <= ip; ++jp) rv[jp] = *(const LAS f32x4*)(Ad + ip * 136 + 4 * jp);
;             asm volatile("" : "+v"(lane_o) :: "memory");
;             f32x2_ a0 = {0.f, 0.f}, a1 = {0.f, 0.f}, a2 = {0.f, 0.f}, a3 = {0.f, 0.f};
; #pragma unroll
;             for (int jp = 0; jp < ip; ++jp) {
;                 const f32x2_ ta = {tr[2 * jp], tr[2 * jp]}, tb = {tr[2 * jp + 1], tr[2 * jp + 1]};
;                 const f32x2_ va = {rv[jp][0], rv[jp][1]}, vb = {rv[jp][2], rv[jp][3]};
;                 if (jp & 1) { a2 += va * ta; a3 += vb * tb; } else { a0 += va * ta; a1 += vb * tb; }
;             }
;             const f32x2_ sum = (a0 + a1) + (a2 + a3);
;             const float t0 = (lane_o == i0 ? 1.f : 0.f) - sum[0];
;             tr[i0] = t0;
;             tr[i0 + 1] = (lane_o == i0 + 1 ? 1.f : 0.f) - sum[1] - rv[ip][1] * t0;
;         }
	v_pk_fma_f32 v[62:63], v[78:79], v[8:9], 0 op_sel_hi:[1,0,0]
	v_pk_fma_f32 v[62:63], v[80:81], v[8:9], v[62:63] op_sel:[0,1,0] op_sel_hi:[1,1,1]
	v_pk_fma_f32 v[62:63], v[82:83], v[10:11], v[62:63] op_sel_hi:[1,0,1]
	v_pk_fma_f32 v[62:63], v[84:85], v[10:11], v[62:63] op_sel:[0,1,0] op_sel_hi:[1,1,1]
	v_pk_fma_f32 v[62:63], v[86:87], v[18:19], v[62:63] op_sel_hi:[1,0,1]
	v_pk_fma_f32 v[62:63], v[88:89], v[18:19], v[62:63] op_sel:[0,1,0] op_sel_hi:[1,1,1]
	v_pk_fma_f32 v[62:63], v[90:91], v[50:51], v[62:63] op_sel_hi:[1,0,1]
	v_pk_fma_f32 v[62:63], v[92:93], v[50:51], v[62:63] op_sel:[0,1,0] op_sel_hi:[1,1,1]
	v_pk_fma_f32 v[62:63], v[98:99], v[58:59], v[62:63] op_sel_hi:[1,0,1]
	v_pk_fma_f32 v[62:63], v[100:101], v[58:59], v[62:63] op_sel:[0,1,0] op_sel_hi:[1,1,1]
	v_pk_fma_f32 v[62:63], v[94:95], v[54:55], v[62:63] op_sel_hi:[1,0,1]
	v_pk_fma_f32 v[62:63], v[96:97], v[54:55], v[62:63] op_sel:[0,1,0] op_sel_hi:[1,1,1]
	s_nop 1
	v_add_f32_dpp v62, v62, v62 quad_perm:[1,0,3,2] row_mask:0xf bank_mask:0xf bound_ctrl:1
	v_add_f32_dpp v63, v63, v63 quad_perm:[1,0,3,2] row_mask:0xf bank_mask:0xf bound_ctrl:1
	s_nop 0
	v_add_f32_dpp v62, v62, v62 quad_perm:[2,3,0,1] row_mask:0xf bank_mask:0xf bound_ctrl:1
	v_add_f32_dpp v63, v63, v63 quad_perm:[2,3,0,1] row_mask:0xf bank_mask:0xf bound_ctrl:1
	s_mov_b64 exec, s[4:5]
	v_pk_add_f32 v[58:59], v[58:59], v[62:63] neg_lo:[0,1] neg_hi:[0,1]
	v_fma_f32 v59, v99, v62, v59
	s_mov_b64 exec, -1
	ds_read_b128 v[78:81], v14 offset:16448
	ds_read_b128 v[82:85], v14 offset:16512
	ds_read_b128 v[86:89], v14 offset:16576
	ds_read_b128 v[90:93], v14 offset:16640
	ds_read_b128 v[94:97], v14 offset:16704
	ds_read_b128 v[98:101], v14 offset:16768
	s_waitcnt lgkmcnt(6)
	v_pk_fma_f32 v[62:63], v[130:131], v[8:9], 0 op_sel_hi:[1,0,0]
	v_pk_fma_f32 v[62:63], v[132:133], v[8:9], v[62:63] op_sel:[0,1,0] op_sel_hi:[1,1,1]
	v_pk_fma_f32 v[62:63], v[38:39], v[10:11], v[62:63] op_sel_hi:[1,0,1]
	v_pk_fma_f32 v[62:63], v[40:41], v[10:11], v[62:63] op_sel:[0,1,0] op_sel_hi:[1,1,1]
	v_pk_fma_f32 v[62:63], v[42:43], v[18:19], v[62:63] op_sel_hi:[1,0,1]
	v_pk_fma_f32 v[62:63], v[44:45], v[18:19], v[62:63] op_sel:[0,1,0] op_sel_hi:[1,1,1]
	v_pk_fma_f32 v[62:63], v[46:47], v[50:51], v[62:63] op_sel_hi:[1,0,1]
	v_pk_fma_f32 v[62:63], v[48:49], v[50:51], v[62:63] op_sel:[0,1,0] op_sel_hi:[1,1,1]
	v_pk_fma_f32 v[62:63], v[102:103], v[54:55], v[62:63] op_sel_hi:[1,0,1]
	v_pk_fma_f32 v[62:63], v[104:105], v[54:55], v[62:63] op_sel:[0,1,0] op_sel_hi:[1,1,1]
	v_pk_fma_f32 v[62:63], v[242:243], v[58:59], v[62:63] op_sel_hi:[1,0,1]
	v_pk_fma_f32 v[62:63], v[244:245], v[58:59], v[62:63] op_sel:[0,1,0] op_sel_hi:[1,1,1]
	s_nop 1
	v_add_f32_dpp v62, v62, v62 quad_perm:[1,0,3,2] row_mask:0xf bank_mask:0xf bound_ctrl:1
	v_add_f32_dpp v63, v63, v63 quad_perm:[1,0,3,2] row_mask:0xf bank_mask:0xf bound_ctrl:1
	s_nop 0
	v_add_f32_dpp v62, v62, v62 quad_perm:[2,3,0,1] row_mask:0xf bank_mask:0xf bound_ctrl:1
	v_add_f32_dpp v63, v63, v63 quad_perm:[2,3,0,1] row_mask:0xf bank_mask:0xf bound_ctrl:1
	s_mov_b64 exec, s[6:7]
	v_pk_add_f32 v[58:59], v[58:59], v[62:63] neg_lo:[0,1] neg_hi:[0,1]
	v_fma_f32 v59, v243, v62, v59
	s_mov_b64 exec, -1
	ds_read_b128 v[130:133], v14 offset:16992
	ds_read_b128 v[38:41], v14 offset:17056
	ds_read_b128 v[42:45], v14 offset:17120
	ds_read_b128 v[46:49], v14 offset:17184
	ds_read_b128 v[102:105], v14 offset:17248
	ds_read_b128 v[242:245], v14 offset:17312
	s_waitcnt lgkmcnt(6)
	v_pk_fma_f32 v[62:63], v[78:79], v[8:9], 0 op_sel_hi:[1,0,0]
	v_pk_fma_f32 v[62:63], v[80:81], v[8:9], v[62:63] op_sel:[0,1,0] op_sel_hi:[1,1,1]
	v_pk_fma_f32 v[62:63], v[82:83], v[10:11], v[62:63] op_sel_hi:[1,0,1]
	v_pk_fma_f32 v[62:63], v[84:85], v[10:11], v[62:63] op_sel:[0,1,0] op_sel_hi:[1,1,1]
	v_pk_fma_f32 v[62:63], v[86:87], v[18:19], v[62:63] op_sel_hi:[1,0,1]
	v_pk_fma_f32 v[62:63], v[88:89], v[18:19], v[62:63] op_sel:[0,1,0] op_sel_hi:[1,1,1]
	v_pk_fma_f32 v[62:63], v[90:91], v[50:51], v[62:63] op_sel_hi:[1,0,1]
	v_pk_fma_f32 v[62:63], v[92:93], v[50:51], v[62:63] op_sel:[0,1,0] op_sel_hi:[1,1,1]
	v_pk_fma_f32 v[62:63], v[94:95], v[54:55], v[62:63] op_sel_hi:[1,0,1]
	v_pk_fma_f32 v[62:63], v[96:97], v[54:55], v[62:63] op_sel:[0,1,0] op_sel_hi:[1,1,1]
	v_pk_fma_f32 v[62:63], v[98:99], v[58:59], v[62:63] op_sel_hi:[1,0,1]
	v_pk_fma_f32 v[62:63], v[100:101], v[58:59], v[62:63] op_sel:[0,1,0] op_sel_hi:[1,1,1]
	s_nop 1
	v_add_f32_dpp v62, v62, v62 quad_perm:[1,0,3,2] row_mask:0xf bank_mask:0xf bound_ctrl:1
	v_add_f32_dpp v63, v63, v63 quad_perm:[1,0,3,2] row_mask:0xf bank_mask:0xf bound_ctrl:1
	s_nop 0
	v_add_f32_dpp v62, v62, v62 quad_perm:[2,3,0,1] row_mask:0xf bank_mask:0xf bound_ctrl:1
	v_add_f32_dpp v63, v63, v63 quad_perm:[2,3,0,1] row_mask:0xf bank_mask:0xf bound_ctrl:1
	s_mov_b64 exec, s[8:9]
	v_pk_add_f32 v[58:59], v[58:59], v[62:63] neg_lo:[0,1] neg_hi:[0,1]
	v_fma_f32 v59, v99, v62, v59
	s_mov_b64 exec, -1
	s_waitcnt lgkmcnt(0)
	v_pk_fma_f32 v[62:63], v[130:131], v[8:9], 0 op_sel_hi:[1,0,0]
	v_pk_fma_f32 v[62:63], v[132:133], v[8:9], v[62:63] op_sel:[0,1,0] op_sel_hi:[1,1,1]
	v_pk_fma_f32 v[62:63], v[38:39], v[10:11], v[62:63] op_sel_hi:[1,0,1]
	v_pk_fma_f32 v[62:63], v[40:41], v[10:11], v[62:63] op_sel:[0,1,0] op_sel_hi:[1,1,1]
	v_pk_fma_f32 v[62:63], v[42:43], v[18:19], v[62:63] op_sel_hi:[1,0,1]
	v_pk_fma_f32 v[62:63], v[44:45], v[18:19], v[62:63] op_sel:[0,1,0] op_sel_hi:[1,1,1]
	v_pk_fma_f32 v[62:63], v[46:47], v[50:51], v[62:63] op_sel_hi:[1,0,1]
	v_pk_fma_f32 v[62:63], v[48:49], v[50:51], v[62:63] op_sel:[0,1,0] op_sel_hi:[1,1,1]
	v_pk_fma_f32 v[62:63], v[102:103], v[54:55], v[62:63] op_sel_hi:[1,0,1]
	v_pk_fma_f32 v[62:63], v[104:105], v[54:55], v[62:63] op_sel:[0,1,0] op_sel_hi:[1,1,1]
	v_pk_fma_f32 v[62:63], v[242:243], v[58:59], v[62:63] op_sel_hi:[1,0,1]
	v_pk_fma_f32 v[62:63], v[244:245], v[58:59], v[62:63] op_sel:[0,1,0] op_sel_hi:[1,1,1]
	s_nop 1
	v_add_f32_dpp v62, v62, v62 quad_perm:[1,0,3,2] row_mask:0xf bank_mask:0xf bound_ctrl:1
	v_add_f32_dpp v63, v63, v63 quad_perm:[1,0,3,2] row_mask:0xf bank_mask:0xf bound_ctrl:1
	s_nop 0
	v_add_f32_dpp v62, v62, v62 quad_perm:[2,3,0,1] row_mask:0xf bank_mask:0xf bound_ctrl:1
	v_add_f32_dpp v63, v63, v63 quad_perm:[2,3,0,1] row_mask:0xf bank_mask:0xf bound_ctrl:1
	s_mov_b64 exec, s[10:11]
	v_pk_add_f32 v[58:59], v[58:59], v[62:63] neg_lo:[0,1] neg_hi:[0,1]
	v_fma_f32 v59, v243, v62, v59
	s_mov_b64 exec, -1
	s_branch .Lfs_outsel
; #define LAS __attribute__((address_space(3)))
;     ...
;     if (w < 2) {
;         const int d = w; const LAS float* Ad = As + d * 4352;
;         float tr[64]; int lane_o = lane;
; #pragma unroll
;         for (int ip = 0; ip < 32; ++ip) {
;             const int i0 = 2 * ip;
;             f32x4 rv[32];
; #pragma unroll
;             for (int jp = 0; jp <= ip; ++jp) rv[jp] = *(const LAS f32x4*)(Ad + ip * 136 + 4 * jp);
;             asm volatile("" : "+v"(lane_o) :: "memory");
;             f32x2_ a0 = {0.f, 0.f}, a1 = {0.f, 0.f}, a2 = {0.f, 0.f}, a3 = {0.f, 0.f};
; #pragma unroll
;             for (int jp = 0; jp < ip; ++jp) {
;                 const f32x2_ ta = {tr[2 * jp], tr[2 * jp]}, tb = {tr[2 * jp + 1], tr[2 * jp + 1]};
;                 const f32x2_ va = {rv[jp][0], rv[jp][1]}, vb = {rv[jp][2], rv[jp][3]};
;                 if (jp & 1) { a2 += va * ta; a3 += vb * tb; } else { a0 += va * ta; a1 += vb * tb; }
;             }
;             const f32x2_ sum = (a0 + a1) + (a2 + a3);
;             const float t0 = (lane_o == i0 ? 1.f : 0.f) - sum[0];
;             tr[i0] = t0;
;             tr[i0 + 1] = (lane_o == i0 + 1 ? 1.f : 0.f) - sum[1] - rv[ip][1] * t0;
;         }
.Lfs_ent2:
	ds_read_b128 v[86:89], v14 offset:8960
	ds_read_b128 v[42:45], v14 offset:9504
	s_waitcnt lgkmcnt(1)
	v_pk_fma_f32 v[62:63], v[86:87], v[18:19], 0 op_sel_hi:[1,0,0]
	v_pk_fma_f32 v[62:63], v[88:89], v[18:19], v[62:63] op_sel:[0,1,0] op_sel_hi:[1,1,1]
	s_nop 1
	v_add_f32_dpp v62, v62, v62 quad_perm:[1,0,3,2] row_mask:0xf bank_mask:0xf bound_ctrl:1
	v_add_f32_dpp v63, v63, v63 quad_perm:[1,0,3,2] row_mask:0xf bank_mask:0xf bound_ctrl:1
	s_nop 0
	v_add_f32_dpp v62, v62, v62 quad_perm:[2,3,0,1] row_mask:0xf bank_mask:0xf bound_ctrl:1
	v_add_f32_dpp v63, v63, v63 quad_perm:[2,3,0,1] row_mask:0xf bank_mask:0xf bound_ctrl:1
	s_mov_b64 exec, s[4:5]
	v_pk_add_f32 v[18:19], v[18:19], v[62:63] neg_lo:[0,1] neg_hi:[0,1]
	v_fma_f32 v19, v87, v62, v19
	s_mov_b64 exec, -1
	ds_read_b128 v[86:89], v14 offset:10048
	s_waitcnt lgkmcnt(1)
	v_pk_fma_f32 v[62:63], v[42:43], v[18:19], 0 op_sel_hi:[1,0,0]
	v_pk_fma_f32 v[62:63], v[44:45], v[18:19], v[62:63] op_sel:[0,1,0] op_sel_hi:[1,1,1]
	s_nop 1
	v_add_f32_dpp v62, v62, v62 quad_perm:[1,0,3,2] row_mask:0xf bank_mask:0xf bound_ctrl:1
	v_add_f32_dpp v63, v63, v63 quad_perm:[1,0,3,2] row_mask:0xf bank_mask:0xf bound_ctrl:1
	s_nop 0
	v_add_f32_dpp v62, v62, v62 quad_perm:[2,3,0,1] row_mask:0xf bank_mask:0xf bound_ctrl:1
	v_add_f32_dpp v63, v63, v63 quad_perm:[2,3,0,1] row_mask:0xf bank_mask:0xf bound_ctrl:1
	s_mov_b64 exec, s[6:7]
	v_pk_add_f32 v[18:19], v[18:19], v[62:63] neg_lo:[0,1] neg_hi:[0,1]
	v_fma_f32 v19, v43, v62, v19
	s_mov_b64 exec, -1
	ds_read_b128 v[42:45], v14 offset:10592
	s_waitcnt lgkmcnt(1)
	v_pk_fma_f32 v[62:63], v[86:87], v[18:19], 0 op_sel_hi:[1,0,0]
	v_pk_fma_f32 v[62:63], v[88:89], v[18:19], v[62:63] op_sel:[0,1,0] op_sel_hi:[1,1,1]
	s_nop 1
	v_add_f32_dpp v62, v62, v62 quad_perm:[1,0,3,2] row_mask:0xf bank_mask:0xf bound_ctrl:1
	v_add_f32_dpp v63, v63, v63 quad_perm:[1,0,3,2] row_mask:0xf bank_mask:0xf bound_ctrl:1
	s_nop 0
	v_add_f32_dpp v62, v62, v62 quad_perm:[2,3,0,1] row_mask:0xf bank_mask:0xf bound_ctrl:1
	v_add_f32_dpp v63, v63, v63 quad_perm:[2,3,0,1] row_mask:0xf bank_mask:0xf bound_ctrl:1
	s_mov_b64 exec, s[8:9]
	v_pk_add_f32 v[18:19], v[18:19], v[62:63] neg_lo:[0,1] neg_hi:[0,1]
	v_fma_f32 v19, v87, v62, v19
	s_mov_b64 exec, -1
	ds_read_b128 v[86:89], v14 offset:11136
	ds_read_b128 v[90:93], v14 offset:11200
	s_waitcnt lgkmcnt(2)
	v_pk_fma_f32 v[62:63], v[42:43], v[18:19], 0 op_sel_hi:[1,0,0]
	v_pk_fma_f32 v[62:63], v[44:45], v[18:19], v[62:63] op_sel:[0,1,0] op_sel_hi:[1,1,1]
	s_nop 1
	v_add_f32_dpp v62, v62, v62 quad_perm:[1,0,3,2] row_mask:0xf bank_mask:0xf bound_ctrl:1
	v_add_f32_dpp v63, v63, v63 quad_perm:[1,0,3,2] row_mask:0xf bank_mask:0xf bound_ctrl:1
	s_nop 0
	v_add_f32_dpp v62, v62, v62 quad_perm:[2,3,0,1] row_mask:0xf bank_mask:0xf bound_ctrl:1
	v_add_f32_dpp v63, v63, v63 quad_perm:[2,3,0,1] row_mask:0xf bank_mask:0xf bound_ctrl:1
	s_mov_b64 exec, s[10:11]
	v_pk_add_f32 v[18:19], v[18:19], v[62:63] neg_lo:[0,1] neg_hi:[0,1]
	v_fma_f32 v19, v43, v62, v19
	s_mov_b64 exec, -1
	ds_read_b128 v[42:45], v14 offset:11680
	ds_read_b128 v[46:49], v14 offset:11744
	s_waitcnt lgkmcnt(2)
	v_pk_fma_f32 v[62:63], v[90:91], v[50:51], 0 op_sel_hi:[1,0,0]
	v_pk_fma_f32 v[62:63], v[92:93], v[50:51], v[62:63] op_sel:[0,1,0] op_sel_hi:[1,1,1]
	v_pk_fma_f32 v[62:63], v[86:87], v[18:19], v[62:63] op_sel_hi:[1,0,1]
	v_pk_fma_f32 v[62:63], v[88:89], v[18:19], v[62:63] op_sel:[0,1,0] op_sel_hi:[1,1,1]
	s_nop 1
	v_add_f32_dpp v62, v62, v62 quad_perm:[1,0,3,2] row_mask:0xf bank_mask:0xf bound_ctrl:1
	v_add_f32_dpp v63, v63, v63 quad_perm:[1,0,3,2] row_mask:0xf bank_mask:0xf bound_ctrl:1
	s_nop 0
	v_add_f32_dpp v62, v62, v62 quad_perm:[2,3,0,1] row_mask:0xf bank_mask:0xf bound_ctrl:1
	v_add_f32_dpp v63, v63, v63 quad_perm:[2,3,0,1] row_mask:0xf bank_mask:0xf bound_ctrl:1
	s_mov_b64 exec, s[4:5]
	v_pk_add_f32 v[50:51], v[50:51], v[62:63] neg_lo:[0,1] neg_hi:[0,1]
	v_fma_f32 v51, v91, v62, v51
	s_mov_b64 exec, -1
	ds_read_b128 v[86:89], v14 offset:12224
	ds_read_b128 v[90:93], v14 offset:12288
	s_waitcnt lgkmcnt(2)
	v_pk_fma_f32 v[62:63], v[42:43], v[18:19], 0 op_sel_hi:[1,0,0]
	v_pk_fma_f32 v[62:63], v[44:45], v[18:19], v[62:63] op_sel:[0,1,0] op_sel_hi:[1,1,1]
	v_pk_fma_f32 v[62:63], v[46:47], v[50:51], v[62:63] op_sel_hi:[1,0,1]
	v_pk_fma_f32 v[62:63], v[48:49], v[50:51], v[62:63] op_sel:[0,1,0] op_sel_hi:[1,1,1]
	s_nop 1
	v_add_f32_dpp v62, v62, v62 quad_perm:[1,0,3,2] row_mask:0xf bank_mask:0xf bound_ctrl:1
	v_add_f32_dpp v63, v63, v63 quad_perm:[1,0,3,2] row_mask:0xf bank_mask:0xf bound_ctrl:1
	s_nop 0
	v_add_f32_dpp v62, v62, v62 quad_perm:[2,3,0,1] row_mask:0xf bank_mask:0xf bound_ctrl:1
	v_add_f32_dpp v63, v63, v63 quad_perm:[2,3,0,1] row_mask:0xf bank_mask:0xf bound_ctrl:1
	s_mov_b64 exec, s[6:7]
	v_pk_add_f32 v[50:51], v[50:51], v[62:63] neg_lo:[0,1] neg_hi:[0,1]
	v_fma_f32 v51, v47, v62, v51
	s_mov_b64 exec, -1
	ds_read_b128 v[42:45], v14 offset:12768
	ds_read_b128 v[46:49], v14 offset:12832
	s_waitcnt lgkmcnt(2)
	v_pk_fma_f32 v[62:63], v[86:87], v[18:19], 0 op_sel_hi:[1,0,0]
	v_pk_fma_f32 v[62:63], v[88:89], v[18:19], v[62:63] op_sel:[0,1,0] op_sel_hi:[1,1,1]
	v_pk_fma_f32 v[62:63], v[90:91], v[50:51], v[62:63] op_sel_hi:[1,0,1]
	v_pk_fma_f32 v[62:63], v[92:93], v[50:51], v[62:63] op_sel:[0,1,0] op_sel_hi:[1,1,1]
	s_nop 1
	v_add_f32_dpp v62, v62, v62 quad_perm:[1,0,3,2] row_mask:0xf bank_mask:0xf bound_ctrl:1
	v_add_f32_dpp v63, v63, v63 quad_perm:[1,0,3,2] row_mask:0xf bank_mask:0xf bound_ctrl:1
	s_nop 0
	v_add_f32_dpp v62, v62, v62 quad_perm:[2,3,0,1] row_mask:0xf bank_mask:0xf bound_ctrl:1
	v_add_f32_dpp v63, v63, v63 quad_perm:[2,3,0,1] row_mask:0xf bank_mask:0xf bound_ctrl:1
	s_mov_b64 exec, s[8:9]
	v_pk_add_f32 v[50:51], v[50:51], v[62:63] neg_lo:[0,1] neg_hi:[0,1]
	v_fma_f32 v51, v91, v62, v51
	s_mov_b64 exec, -1
	ds_read_b128 v[86:89], v14 offset:13312
	ds_read_b128 v[90:93], v14 offset:13376
	ds_read_b128 v[94:97], v14 offset:13440
	s_waitcnt lgkmcnt(3)
; #define LAS __attribute__((address_space(3)))
;     ...
;     if (w < 2) {
;         const int d = w; const LAS float* Ad = As + d * 4352;
;         float tr[64]; int lane_o = lane;
; #pragma unroll
;         for (int ip = 0; ip < 32; ++ip) {
;             const int i0 = 2 * ip;
;             f32x4 rv[32];
; #pragma unroll
;             for (int jp = 0; jp <= ip; ++jp) rv[jp] = *(const LAS f32x4*)(Ad + ip * 136 + 4 * jp);
;             asm volatile("" : "+v"(lane_o) :: "memory");
;             f32x2_ a0 = {0.f, 0.f}, a1 = {0.f, 0.f}, a2 = {0.f, 0.f}, a3 = {0.f, 0.f};
; #pragma unroll
;             for (int jp = 0; jp < ip; ++jp) {
;                 const f32x2_ ta = {tr[2 * jp], tr[2 * jp]}, tb = {tr[2 * jp + 1], tr[2 * jp + 1]};
;                 const f32x2_ va = {rv[jp][0], rv[jp][1]}, vb = {rv[jp][2], rv[jp][3]};
;                 if (jp & 1) { a2 += va * ta; a3 += vb * tb; } else { a0 += va * ta; a1 += vb * tb; }
;             }
;             const f32x2_ sum = (a0 + a1) + (a2 + a3);
;             const float t0 = (lane_o == i0 ? 1.f : 0.f) - sum[0];
;             tr[i0] = t0;
;             tr[i0 + 1] = (lane_o == i0 + 1 ? 1.f : 0.f) - sum[1] - rv[ip][1] * t0;
;         }
	v_pk_fma_f32 v[62:63], v[42:43], v[18:19], 0 op_sel_hi:[1,0,0]
	v_pk_fma_f32 v[62:63], v[44:45], v[18:19], v[62:63] op_sel:[0,1,0] op_sel_hi:[1,1,1]
	v_pk_fma_f32 v[62:63], v[46:47], v[50:51], v[62:63] op_sel_hi:[1,0,1]
	v_pk_fma_f32 v[62:63], v[48:49], v[50:51], v[62:63] op_sel:[0,1,0] op_sel_hi:[1,1,1]
	s_nop 1
	v_add_f32_dpp v62, v62, v62 quad_perm:[1,0,3,2] row_mask:0xf bank_mask:0xf bound_ctrl:1
	v_add_f32_dpp v63, v63, v63 quad_perm:[1,0,3,2] row_mask:0xf bank_mask:0xf bound_ctrl:1
	s_nop 0
	v_add_f32_dpp v62, v62, v62 quad_perm:[2,3,0,1] row_mask:0xf bank_mask:0xf bound_ctrl:1
	v_add_f32_dpp v63, v63, v63 quad_perm:[2,3,0,1] row_mask:0xf bank_mask:0xf bound_ctrl:1
	s_mov_b64 exec, s[10:11]
	v_pk_add_f32 v[50:51], v[50:51], v[62:63] neg_lo:[0,1] neg_hi:[0,1]
	v_fma_f32 v51, v47, v62, v51
	s_mov_b64 exec, -1
	ds_read_b128 v[42:45], v14 offset:13856
	ds_read_b128 v[46:49], v14 offset:13920
	ds_read_b128 v[102:105], v14 offset:13984
	s_waitcnt lgkmcnt(3)
	v_pk_fma_f32 v[62:63], v[86:87], v[18:19], 0 op_sel_hi:[1,0,0]
	v_pk_fma_f32 v[62:63], v[88:89], v[18:19], v[62:63] op_sel:[0,1,0] op_sel_hi:[1,1,1]
	v_pk_fma_f32 v[62:63], v[94:95], v[54:55], v[62:63] op_sel_hi:[1,0,1]
	v_pk_fma_f32 v[62:63], v[96:97], v[54:55], v[62:63] op_sel:[0,1,0] op_sel_hi:[1,1,1]
	v_pk_fma_f32 v[62:63], v[90:91], v[50:51], v[62:63] op_sel_hi:[1,0,1]
	v_pk_fma_f32 v[62:63], v[92:93], v[50:51], v[62:63] op_sel:[0,1,0] op_sel_hi:[1,1,1]
	s_nop 1
	v_add_f32_dpp v62, v62, v62 quad_perm:[1,0,3,2] row_mask:0xf bank_mask:0xf bound_ctrl:1
	v_add_f32_dpp v63, v63, v63 quad_perm:[1,0,3,2] row_mask:0xf bank_mask:0xf bound_ctrl:1
	s_nop 0
	v_add_f32_dpp v62, v62, v62 quad_perm:[2,3,0,1] row_mask:0xf bank_mask:0xf bound_ctrl:1
	v_add_f32_dpp v63, v63, v63 quad_perm:[2,3,0,1] row_mask:0xf bank_mask:0xf bound_ctrl:1
	s_mov_b64 exec, s[4:5]
	v_pk_add_f32 v[54:55], v[54:55], v[62:63] neg_lo:[0,1] neg_hi:[0,1]
	v_fma_f32 v55, v95, v62, v55
	s_mov_b64 exec, -1
	ds_read_b128 v[86:89], v14 offset:14400
	ds_read_b128 v[90:93], v14 offset:14464
	ds_read_b128 v[94:97], v14 offset:14528
	s_waitcnt lgkmcnt(3)
	v_pk_fma_f32 v[62:63], v[42:43], v[18:19], 0 op_sel_hi:[1,0,0]
	v_pk_fma_f32 v[62:63], v[44:45], v[18:19], v[62:63] op_sel:[0,1,0] op_sel_hi:[1,1,1]
	v_pk_fma_f32 v[62:63], v[46:47], v[50:51], v[62:63] op_sel_hi:[1,0,1]
	v_pk_fma_f32 v[62:63], v[48:49], v[50:51], v[62:63] op_sel:[0,1,0] op_sel_hi:[1,1,1]
	v_pk_fma_f32 v[62:63], v[102:103], v[54:55], v[62:63] op_sel_hi:[1,0,1]
	v_pk_fma_f32 v[62:63], v[104:105], v[54:55], v[62:63] op_sel:[0,1,0] op_sel_hi:[1,1,1]
	s_nop 1
	v_add_f32_dpp v62, v62, v62 quad_perm:[1,0,3,2] row_mask:0xf bank_mask:0xf bound_ctrl:1
	v_add_f32_dpp v63, v63, v63 quad_perm:[1,0,3,2] row_mask:0xf bank_mask:0xf bound_ctrl:1
	s_nop 0
	v_add_f32_dpp v62, v62, v62 quad_perm:[2,3,0,1] row_mask:0xf bank_mask:0xf bound_ctrl:1
	v_add_f32_dpp v63, v63, v63 quad_perm:[2,3,0,1] row_mask:0xf bank_mask:0xf bound_ctrl:1
	s_mov_b64 exec, s[6:7]
	v_pk_add_f32 v[54:55], v[54:55], v[62:63] neg_lo:[0,1] neg_hi:[0,1]
	v_fma_f32 v55, v103, v62, v55
	s_mov_b64 exec, -1
	ds_read_b128 v[42:45], v14 offset:14944
	ds_read_b128 v[46:49], v14 offset:15008
	ds_read_b128 v[102:105], v14 offset:15072
	s_waitcnt lgkmcnt(3)
	v_pk_fma_f32 v[62:63], v[86:87], v[18:19], 0 op_sel_hi:[1,0,0]
	v_pk_fma_f32 v[62:63], v[88:89], v[18:19], v[62:63] op_sel:[0,1,0] op_sel_hi:[1,1,1]
	v_pk_fma_f32 v[62:63], v[90:91], v[50:51], v[62:63] op_sel_hi:[1,0,1]
	v_pk_fma_f32 v[62:63], v[92:93], v[50:51], v[62:63] op_sel:[0,1,0] op_sel_hi:[1,1,1]
	v_pk_fma_f32 v[62:63], v[94:95], v[54:55], v[62:63] op_sel_hi:[1,0,1]
	v_pk_fma_f32 v[62:63], v[96:97], v[54:55], v[62:63] op_sel:[0,1,0] op_sel_hi:[1,1,1]
	s_nop 1
	v_add_f32_dpp v62, v62, v62 quad_perm:[1,0,3,2] row_mask:0xf bank_mask:0xf bound_ctrl:1
	v_add_f32_dpp v63, v63, v63 quad_perm:[1,0,3,2] row_mask:0xf bank_mask:0xf bound_ctrl:1
	s_nop 0
	v_add_f32_dpp v62, v62, v62 quad_perm:[2,3,0,1] row_mask:0xf bank_mask:0xf bound_ctrl:1
	v_add_f32_dpp v63, v63, v63 quad_perm:[2,3,0,1] row_mask:0xf bank_mask:0xf bound_ctrl:1
	s_mov_b64 exec, s[8:9]
	v_pk_add_f32 v[54:55], v[54:55], v[62:63] neg_lo:[0,1] neg_hi:[0,1]
	v_fma_f32 v55, v95, v62, v55
	s_mov_b64 exec, -1
	ds_read_b128 v[86:89], v14 offset:15488
	ds_read_b128 v[90:93], v14 offset:15552
	ds_read_b128 v[94:97], v14 offset:15616
	ds_read_b128 v[98:101], v14 offset:15680
	s_waitcnt lgkmcnt(4)
	v_pk_fma_f32 v[62:63], v[42:43], v[18:19], 0 op_sel_hi:[1,0,0]
	v_pk_fma_f32 v[62:63], v[44:45], v[18:19], v[62:63] op_sel:[0,1,0] op_sel_hi:[1,1,1]
	v_pk_fma_f32 v[62:63], v[46:47], v[50:51], v[62:63] op_sel_hi:[1,0,1]
	v_pk_fma_f32 v[62:63], v[48:49], v[50:51], v[62:63] op_sel:[0,1,0] op_sel_hi:[1,1,1]
	v_pk_fma_f32 v[62:63], v[102:103], v[54:55], v[62:63] op_sel_hi:[1,0,1]
	v_pk_fma_f32 v[62:63], v[104:105], v[54:55], v[62:63] op_sel:[0,1,0] op_sel_hi:[1,1,1]
	s_nop 1
	v_add_f32_dpp v62, v62, v62 quad_perm:[1,0,3,2] row_mask:0xf bank_mask:0xf bound_ctrl:1
	v_add_f32_dpp v63, v63, v63 quad_perm:[1,0,3,2] row_mask:0xf bank_mask:0xf bound_ctrl:1
	s_nop 0
	v_add_f32_dpp v62, v62, v62 quad_perm:[2,3,0,1] row_mask:0xf bank_mask:0xf bound_ctrl:1
	v_add_f32_dpp v63, v63, v63 quad_perm:[2,3,0,1] row_mask:0xf bank_mask:0xf bound_ctrl:1
	s_mov_b64 exec, s[10:11]
	v_pk_add_f32 v[54:55], v[54:55], v[62:63] neg_lo:[0,1] neg_hi:[0,1]
	v_fma_f32 v55, v103, v62, v55
	s_mov_b64 exec, -1
	ds_read_b128 v[42:45], v14 offset:16032
	ds_read_b128 v[46:49], v14 offset:16096
	ds_read_b128 v[102:105], v14 offset:16160
	ds_read_b128 v[242:245], v14 offset:16224
	s_waitcnt lgkmcnt(4)
; #define LAS __attribute__((address_space(3)))
;     ...
;     if (w < 2) {
;         const int d = w; const LAS float* Ad = As + d * 4352;
;         float tr[64]; int lane_o = lane;
; #pragma unroll
;         for (int ip = 0; ip < 32; ++ip) {
;             const int i0 = 2 * ip;
;             f32x4 rv[32];
; #pragma unroll
;             for (int jp = 0; jp <= ip; ++jp) rv[jp] = *(const LAS f32x4*)(Ad + ip * 136 + 4 * jp);
;             asm volatile("" : "+v"(lane_o) :: "memory");
;             f32x2_ a0 = {0.f, 0.f}, a1 = {0.f, 0.f}, a2 = {0.f, 0.f}, a3 = {0.f, 0.f};
; #pragma unroll
;             for (int jp = 0; jp < ip; ++jp) {
;                 const f32x2_ ta = {tr[2 * jp], tr[2 * jp]}, tb = {tr[2 * jp + 1], tr[2 * jp + 1]};
;                 const f32x2_ va = {rv[jp][0], rv[jp][1]}, vb = {rv[jp][2], rv[jp][3]};
;                 if (jp & 1) { a2 += va * ta; a3 += vb * tb; } else { a0 += va * ta; a1 += vb * tb; }
;             }
;             const f32x2_ sum = (a0 + a1) + (a2 + a3);
;             const float t0 = (lane_o == i0 ? 1.f : 0.f) - sum[0];
;             tr[i0] = t0;
;             tr[i0 + 1] = (lane_o == i0 + 1 ? 1.f : 0.f) - sum[1] - rv[ip][1] * t0;
;         }
	v_pk_fma_f32 v[62:63], v[86:87], v[18:19], 0 op_sel_hi:[1,0,0]
	v_pk_fma_f32 v[62:63], v[88:89], v[18:19], v[62:63] op_sel:[0,1,0] op_sel_hi:[1,1,1]
	v_pk_fma_f32 v[62:63], v[90:91], v[50:51], v[62:63] op_sel_hi:[1,0,1]
	v_pk_fma_f32 v[62:63], v[92:93], v[50:51], v[62:63] op_sel:[0,1,0] op_sel_hi:[1,1,1]
	v_pk_fma_f32 v[62:63], v[98:99], v[58:59], v[62:63] op_sel_hi:[1,0,1]
	v_pk_fma_f32 v[62:63], v[100:101], v[58:59], v[62:63] op_sel:[0,1,0] op_sel_hi:[1,1,1]
	v_pk_fma_f32 v[62:63], v[94:95], v[54:55], v[62:63] op_sel_hi:[1,0,1]
	v_pk_fma_f32 v[62:63], v[96:97], v[54:55], v[62:63] op_sel:[0,1,0] op_sel_hi:[1,1,1]
	s_nop 1
	v_add_f32_dpp v62, v62, v62 quad_perm:[1,0,3,2] row_mask:0xf bank_mask:0xf bound_ctrl:1
	v_add_f32_dpp v63, v63, v63 quad_perm:[1,0,3,2] row_mask:0xf bank_mask:0xf bound_ctrl:1
	s_nop 0
	v_add_f32_dpp v62, v62, v62 quad_perm:[2,3,0,1] row_mask:0xf bank_mask:0xf bound_ctrl:1
	v_add_f32_dpp v63, v63, v63 quad_perm:[2,3,0,1] row_mask:0xf bank_mask:0xf bound_ctrl:1
	s_mov_b64 exec, s[4:5]
	v_pk_add_f32 v[58:59], v[58:59], v[62:63] neg_lo:[0,1] neg_hi:[0,1]
	v_fma_f32 v59, v99, v62, v59
	s_mov_b64 exec, -1
	ds_read_b128 v[86:89], v14 offset:16576
	ds_read_b128 v[90:93], v14 offset:16640
	ds_read_b128 v[94:97], v14 offset:16704
	ds_read_b128 v[98:101], v14 offset:16768
	s_waitcnt lgkmcnt(4)
	v_pk_fma_f32 v[62:63], v[42:43], v[18:19], 0 op_sel_hi:[1,0,0]
	v_pk_fma_f32 v[62:63], v[44:45], v[18:19], v[62:63] op_sel:[0,1,0] op_sel_hi:[1,1,1]
	v_pk_fma_f32 v[62:63], v[46:47], v[50:51], v[62:63] op_sel_hi:[1,0,1]
	v_pk_fma_f32 v[62:63], v[48:49], v[50:51], v[62:63] op_sel:[0,1,0] op_sel_hi:[1,1,1]
	v_pk_fma_f32 v[62:63], v[102:103], v[54:55], v[62:63] op_sel_hi:[1,0,1]
	v_pk_fma_f32 v[62:63], v[104:105], v[54:55], v[62:63] op_sel:[0,1,0] op_sel_hi:[1,1,1]
	v_pk_fma_f32 v[62:63], v[242:243], v[58:59], v[62:63] op_sel_hi:[1,0,1]
	v_pk_fma_f32 v[62:63], v[244:245], v[58:59], v[62:63] op_sel:[0,1,0] op_sel_hi:[1,1,1]
	s_nop 1
	v_add_f32_dpp v62, v62, v62 quad_perm:[1,0,3,2] row_mask:0xf bank_mask:0xf bound_ctrl:1
	v_add_f32_dpp v63, v63, v63 quad_perm:[1,0,3,2] row_mask:0xf bank_mask:0xf bound_ctrl:1
	s_nop 0
	v_add_f32_dpp v62, v62, v62 quad_perm:[2,3,0,1] row_mask:0xf bank_mask:0xf bound_ctrl:1
	v_add_f32_dpp v63, v63, v63 quad_perm:[2,3,0,1] row_mask:0xf bank_mask:0xf bound_ctrl:1
	s_mov_b64 exec, s[6:7]
	v_pk_add_f32 v[58:59], v[58:59], v[62:63] neg_lo:[0,1] neg_hi:[0,1]
	v_fma_f32 v59, v243, v62, v59
	s_mov_b64 exec, -1
	ds_read_b128 v[42:45], v14 offset:17120
	ds_read_b128 v[46:49], v14 offset:17184
	ds_read_b128 v[102:105], v14 offset:17248
	ds_read_b128 v[242:245], v14 offset:17312
	s_waitcnt lgkmcnt(4)
	v_pk_fma_f32 v[62:63], v[86:87], v[18:19], 0 op_sel_hi:[1,0,0]
	v_pk_fma_f32 v[62:63], v[88:89], v[18:19], v[62:63] op_sel:[0,1,0] op_sel_hi:[1,1,1]
	v_pk_fma_f32 v[62:63], v[90:91], v[50:51], v[62:63] op_sel_hi:[1,0,1]
	v_pk_fma_f32 v[62:63], v[92:93], v[50:51], v[62:63] op_sel:[0,1,0] op_sel_hi:[1,1,1]
	v_pk_fma_f32 v[62:63], v[94:95], v[54:55], v[62:63] op_sel_hi:[1,0,1]
	v_pk_fma_f32 v[62:63], v[96:97], v[54:55], v[62:63] op_sel:[0,1,0] op_sel_hi:[1,1,1]
	v_pk_fma_f32 v[62:63], v[98:99], v[58:59], v[62:63] op_sel_hi:[1,0,1]
	v_pk_fma_f32 v[62:63], v[100:101], v[58:59], v[62:63] op_sel:[0,1,0] op_sel_hi:[1,1,1]
	s_nop 1
	v_add_f32_dpp v62, v62, v62 quad_perm:[1,0,3,2] row_mask:0xf bank_mask:0xf bound_ctrl:1
	v_add_f32_dpp v63, v63, v63 quad_perm:[1,0,3,2] row_mask:0xf bank_mask:0xf bound_ctrl:1
	s_nop 0
	v_add_f32_dpp v62, v62, v62 quad_perm:[2,3,0,1] row_mask:0xf bank_mask:0xf bound_ctrl:1
	v_add_f32_dpp v63, v63, v63 quad_perm:[2,3,0,1] row_mask:0xf bank_mask:0xf bound_ctrl:1
	s_mov_b64 exec, s[8:9]
	v_pk_add_f32 v[58:59], v[58:59], v[62:63] neg_lo:[0,1] neg_hi:[0,1]
	v_fma_f32 v59, v99, v62, v59
	s_mov_b64 exec, -1
	s_waitcnt lgkmcnt(0)
	v_pk_fma_f32 v[62:63], v[42:43], v[18:19], 0 op_sel_hi:[1,0,0]
	v_pk_fma_f32 v[62:63], v[44:45], v[18:19], v[62:63] op_sel:[0,1,0] op_sel_hi:[1,1,1]
	v_pk_fma_f32 v[62:63], v[46:47], v[50:51], v[62:63] op_sel_hi:[1,0,1]
	v_pk_fma_f32 v[62:63], v[48:49], v[50:51], v[62:63] op_sel:[0,1,0] op_sel_hi:[1,1,1]
	v_pk_fma_f32 v[62:63], v[102:103], v[54:55], v[62:63] op_sel_hi:[1,0,1]
	v_pk_fma_f32 v[62:63], v[104:105], v[54:55], v[62:63] op_sel:[0,1,0] op_sel_hi:[1,1,1]
	v_pk_fma_f32 v[62:63], v[242:243], v[58:59], v[62:63] op_sel_hi:[1,0,1]
	v_pk_fma_f32 v[62:63], v[244:245], v[58:59], v[62:63] op_sel:[0,1,0] op_sel_hi:[1,1,1]
	s_nop 1
	v_add_f32_dpp v62, v62, v62 quad_perm:[1,0,3,2] row_mask:0xf bank_mask:0xf bound_ctrl:1
	v_add_f32_dpp v63, v63, v63 quad_perm:[1,0,3,2] row_mask:0xf bank_mask:0xf bound_ctrl:1
	s_nop 0
	v_add_f32_dpp v62, v62, v62 quad_perm:[2,3,0,1] row_mask:0xf bank_mask:0xf bound_ctrl:1
	v_add_f32_dpp v63, v63, v63 quad_perm:[2,3,0,1] row_mask:0xf bank_mask:0xf bound_ctrl:1
	s_mov_b64 exec, s[10:11]
	v_pk_add_f32 v[58:59], v[58:59], v[62:63] neg_lo:[0,1] neg_hi:[0,1]
	v_fma_f32 v59, v243, v62, v59
	s_mov_b64 exec, -1
	s_branch .Lfs_outsel
; #define LAS __attribute__((address_space(3)))
;     ...
;     if (w < 2) {
;         const int d = w; const LAS float* Ad = As + d * 4352;
;         float tr[64]; int lane_o = lane;
; #pragma unroll
;         for (int ip = 0; ip < 32; ++ip) {
;             const int i0 = 2 * ip;
;             f32x4 rv[32];
; #pragma unroll
;             for (int jp = 0; jp <= ip; ++jp) rv[jp] = *(const LAS f32x4*)(Ad + ip * 136 + 4 * jp);
;             asm volatile("" : "+v"(lane_o) :: "memory");
;             f32x2_ a0 = {0.f, 0.f}, a1 = {0.f, 0.f}, a2 = {0.f, 0.f}, a3 = {0.f, 0.f};
; #pragma unroll
;             for (int jp = 0; jp < ip; ++jp) {
;                 const f32x2_ ta = {tr[2 * jp], tr[2 * jp]}, tb = {tr[2 * jp + 1], tr[2 * jp + 1]};
;                 const f32x2_ va = {rv[jp][0], rv[jp][1]}, vb = {rv[jp][2], rv[jp][3]};
;                 if (jp & 1) { a2 += va * ta; a3 += vb * tb; } else { a0 += va * ta; a1 += vb * tb; }
;             }
;             const f32x2_ sum = (a0 + a1) + (a2 + a3);
;             const float t0 = (lane_o == i0 ? 1.f : 0.f) - sum[0];
;             tr[i0] = t0;
;             tr[i0 + 1] = (lane_o == i0 + 1 ? 1.f : 0.f) - sum[1] - rv[ip][1] * t0;
;         }
.Lfs_ent3:
	ds_read_b128 v[94:97], v14 offset:13440
	ds_read_b128 v[102:105], v14 offset:13984
	s_waitcnt lgkmcnt(1)
	v_pk_fma_f32 v[62:63], v[94:95], v[54:55], 0 op_sel_hi:[1,0,0]
	v_pk_fma_f32 v[62:63], v[96:97], v[54:55], v[62:63] op_sel:[0,1,0] op_sel_hi:[1,1,1]
	s_nop 1
	v_add_f32_dpp v62, v62, v62 quad_perm:[1,0,3,2] row_mask:0xf bank_mask:0xf bound_ctrl:1
	v_add_f32_dpp v63, v63, v63 quad_perm:[1,0,3,2] row_mask:0xf bank_mask:0xf bound_ctrl:1
	s_nop 0
	v_add_f32_dpp v62, v62, v62 quad_perm:[2,3,0,1] row_mask:0xf bank_mask:0xf bound_ctrl:1
	v_add_f32_dpp v63, v63, v63 quad_perm:[2,3,0,1] row_mask:0xf bank_mask:0xf bound_ctrl:1
	s_mov_b64 exec, s[4:5]
	v_pk_add_f32 v[54:55], v[54:55], v[62:63] neg_lo:[0,1] neg_hi:[0,1]
	v_fma_f32 v55, v95, v62, v55
	s_mov_b64 exec, -1
	ds_read_b128 v[94:97], v14 offset:14528
	s_waitcnt lgkmcnt(1)
	v_pk_fma_f32 v[62:63], v[102:103], v[54:55], 0 op_sel_hi:[1,0,0]
	v_pk_fma_f32 v[62:63], v[104:105], v[54:55], v[62:63] op_sel:[0,1,0] op_sel_hi:[1,1,1]
	s_nop 1
	v_add_f32_dpp v62, v62, v62 quad_perm:[1,0,3,2] row_mask:0xf bank_mask:0xf bound_ctrl:1
	v_add_f32_dpp v63, v63, v63 quad_perm:[1,0,3,2] row_mask:0xf bank_mask:0xf bound_ctrl:1
	s_nop 0
	v_add_f32_dpp v62, v62, v62 quad_perm:[2,3,0,1] row_mask:0xf bank_mask:0xf bound_ctrl:1
	v_add_f32_dpp v63, v63, v63 quad_perm:[2,3,0,1] row_mask:0xf bank_mask:0xf bound_ctrl:1
	s_mov_b64 exec, s[6:7]
	v_pk_add_f32 v[54:55], v[54:55], v[62:63] neg_lo:[0,1] neg_hi:[0,1]
	v_fma_f32 v55, v103, v62, v55
	s_mov_b64 exec, -1
	ds_read_b128 v[102:105], v14 offset:15072
	s_waitcnt lgkmcnt(1)
	v_pk_fma_f32 v[62:63], v[94:95], v[54:55], 0 op_sel_hi:[1,0,0]
	v_pk_fma_f32 v[62:63], v[96:97], v[54:55], v[62:63] op_sel:[0,1,0] op_sel_hi:[1,1,1]
	s_nop 1
	v_add_f32_dpp v62, v62, v62 quad_perm:[1,0,3,2] row_mask:0xf bank_mask:0xf bound_ctrl:1
	v_add_f32_dpp v63, v63, v63 quad_perm:[1,0,3,2] row_mask:0xf bank_mask:0xf bound_ctrl:1
	s_nop 0
	v_add_f32_dpp v62, v62, v62 quad_perm:[2,3,0,1] row_mask:0xf bank_mask:0xf bound_ctrl:1
	v_add_f32_dpp v63, v63, v63 quad_perm:[2,3,0,1] row_mask:0xf bank_mask:0xf bound_ctrl:1
	s_mov_b64 exec, s[8:9]
	v_pk_add_f32 v[54:55], v[54:55], v[62:63] neg_lo:[0,1] neg_hi:[0,1]
	v_fma_f32 v55, v95, v62, v55
	s_mov_b64 exec, -1
	ds_read_b128 v[94:97], v14 offset:15616
	ds_read_b128 v[98:101], v14 offset:15680
	s_waitcnt lgkmcnt(2)
	v_pk_fma_f32 v[62:63], v[102:103], v[54:55], 0 op_sel_hi:[1,0,0]
	v_pk_fma_f32 v[62:63], v[104:105], v[54:55], v[62:63] op_sel:[0,1,0] op_sel_hi:[1,1,1]
	s_nop 1
	v_add_f32_dpp v62, v62, v62 quad_perm:[1,0,3,2] row_mask:0xf bank_mask:0xf bound_ctrl:1
	v_add_f32_dpp v63, v63, v63 quad_perm:[1,0,3,2] row_mask:0xf bank_mask:0xf bound_ctrl:1
	s_nop 0
	v_add_f32_dpp v62, v62, v62 quad_perm:[2,3,0,1] row_mask:0xf bank_mask:0xf bound_ctrl:1
	v_add_f32_dpp v63, v63, v63 quad_perm:[2,3,0,1] row_mask:0xf bank_mask:0xf bound_ctrl:1
	s_mov_b64 exec, s[10:11]
	v_pk_add_f32 v[54:55], v[54:55], v[62:63] neg_lo:[0,1] neg_hi:[0,1]
	v_fma_f32 v55, v103, v62, v55
	s_mov_b64 exec, -1
	ds_read_b128 v[102:105], v14 offset:16160
	ds_read_b128 v[242:245], v14 offset:16224
	s_waitcnt lgkmcnt(2)
	v_pk_fma_f32 v[62:63], v[98:99], v[58:59], 0 op_sel_hi:[1,0,0]
	v_pk_fma_f32 v[62:63], v[100:101], v[58:59], v[62:63] op_sel:[0,1,0] op_sel_hi:[1,1,1]
	v_pk_fma_f32 v[62:63], v[94:95], v[54:55], v[62:63] op_sel_hi:[1,0,1]
	v_pk_fma_f32 v[62:63], v[96:97], v[54:55], v[62:63] op_sel:[0,1,0] op_sel_hi:[1,1,1]
	s_nop 1
	v_add_f32_dpp v62, v62, v62 quad_perm:[1,0,3,2] row_mask:0xf bank_mask:0xf bound_ctrl:1
	v_add_f32_dpp v63, v63, v63 quad_perm:[1,0,3,2] row_mask:0xf bank_mask:0xf bound_ctrl:1
	s_nop 0
	v_add_f32_dpp v62, v62, v62 quad_perm:[2,3,0,1] row_mask:0xf bank_mask:0xf bound_ctrl:1
	v_add_f32_dpp v63, v63, v63 quad_perm:[2,3,0,1] row_mask:0xf bank_mask:0xf bound_ctrl:1
	s_mov_b64 exec, s[4:5]
	v_pk_add_f32 v[58:59], v[58:59], v[62:63] neg_lo:[0,1] neg_hi:[0,1]
	v_fma_f32 v59, v99, v62, v59
	s_mov_b64 exec, -1
	ds_read_b128 v[94:97], v14 offset:16704
	ds_read_b128 v[98:101], v14 offset:16768
	s_waitcnt lgkmcnt(2)
	v_pk_fma_f32 v[62:63], v[102:103], v[54:55], 0 op_sel_hi:[1,0,0]
	v_pk_fma_f32 v[62:63], v[104:105], v[54:55], v[62:63] op_sel:[0,1,0] op_sel_hi:[1,1,1]
	v_pk_fma_f32 v[62:63], v[242:243], v[58:59], v[62:63] op_sel_hi:[1,0,1]
	v_pk_fma_f32 v[62:63], v[244:245], v[58:59], v[62:63] op_sel:[0,1,0] op_sel_hi:[1,1,1]
	s_nop 1
	v_add_f32_dpp v62, v62, v62 quad_perm:[1,0,3,2] row_mask:0xf bank_mask:0xf bound_ctrl:1
	v_add_f32_dpp v63, v63, v63 quad_perm:[1,0,3,2] row_mask:0xf bank_mask:0xf bound_ctrl:1
	s_nop 0
	v_add_f32_dpp v62, v62, v62 quad_perm:[2,3,0,1] row_mask:0xf bank_mask:0xf bound_ctrl:1
	v_add_f32_dpp v63, v63, v63 quad_perm:[2,3,0,1] row_mask:0xf bank_mask:0xf bound_ctrl:1
	s_mov_b64 exec, s[6:7]
	v_pk_add_f32 v[58:59], v[58:59], v[62:63] neg_lo:[0,1] neg_hi:[0,1]
	v_fma_f32 v59, v243, v62, v59
	s_mov_b64 exec, -1
	ds_read_b128 v[102:105], v14 offset:17248
	ds_read_b128 v[242:245], v14 offset:17312
	s_waitcnt lgkmcnt(2)
	v_pk_fma_f32 v[62:63], v[94:95], v[54:55], 0 op_sel_hi:[1,0,0]
	v_pk_fma_f32 v[62:63], v[96:97], v[54:55], v[62:63] op_sel:[0,1,0] op_sel_hi:[1,1,1]
	v_pk_fma_f32 v[62:63], v[98:99], v[58:59], v[62:63] op_sel_hi:[1,0,1]
	v_pk_fma_f32 v[62:63], v[100:101], v[58:59], v[62:63] op_sel:[0,1,0] op_sel_hi:[1,1,1]
	s_nop 1
	v_add_f32_dpp v62, v62, v62 quad_perm:[1,0,3,2] row_mask:0xf bank_mask:0xf bound_ctrl:1
	v_add_f32_dpp v63, v63, v63 quad_perm:[1,0,3,2] row_mask:0xf bank_mask:0xf bound_ctrl:1
	s_nop 0
	v_add_f32_dpp v62, v62, v62 quad_perm:[2,3,0,1] row_mask:0xf bank_mask:0xf bound_ctrl:1
	v_add_f32_dpp v63, v63, v63 quad_perm:[2,3,0,1] row_mask:0xf bank_mask:0xf bound_ctrl:1
	s_mov_b64 exec, s[8:9]
	v_pk_add_f32 v[58:59], v[58:59], v[62:63] neg_lo:[0,1] neg_hi:[0,1]
	v_fma_f32 v59, v99, v62, v59
	s_mov_b64 exec, -1
	s_waitcnt lgkmcnt(0)
	v_pk_fma_f32 v[62:63], v[102:103], v[54:55], 0 op_sel_hi:[1,0,0]
	v_pk_fma_f32 v[62:63], v[104:105], v[54:55], v[62:63] op_sel:[0,1,0] op_sel_hi:[1,1,1]
	v_pk_fma_f32 v[62:63], v[242:243], v[58:59], v[62:63] op_sel_hi:[1,0,1]
	v_pk_fma_f32 v[62:63], v[244:245], v[58:59], v[62:63] op_sel:[0,1,0] op_sel_hi:[1,1,1]
	s_nop 1
	v_add_f32_dpp v62, v62, v62 quad_perm:[1,0,3,2] row_mask:0xf bank_mask:0xf bound_ctrl:1
	v_add_f32_dpp v63, v63, v63 quad_perm:[1,0,3,2] row_mask:0xf bank_mask:0xf bound_ctrl:1
	s_nop 0
	v_add_f32_dpp v62, v62, v62 quad_perm:[2,3,0,1] row_mask:0xf bank_mask:0xf bound_ctrl:1
	v_add_f32_dpp v63, v63, v63 quad_perm:[2,3,0,1] row_mask:0xf bank_mask:0xf bound_ctrl:1
	s_mov_b64 exec, s[10:11]
	v_pk_add_f32 v[58:59], v[58:59], v[62:63] neg_lo:[0,1] neg_hi:[0,1]
	v_fma_f32 v59, v243, v62, v59
	s_mov_b64 exec, -1
; #define LAS __attribute__((address_space(3)))
; __device__ __forceinline__ unsigned f2bf(float f) { return pk2(f, 0.f) & 0xffffu; }
; __device__ __forceinline__ float fexp(float x) { return __builtin_amdgcn_exp2f(x * 1.4426950408889634f); }
;     ...
;         const int pb = d ? 63 - lane : lane; const float sb = bS[d * 64 + pb], sbe = sb * fexp(gcS[d * 64 + pb]);
;         LAS bf16_t* T0 = Tb + d * 9216; LAS bf16_t* T1 = T0 + 4608;
; #pragma unroll
;         for (int i = 0; i < 64; ++i) { const int pa = d ? 63 - i : i; T0[pa * 72 + pb] = (bf16_t)f2bf(tr[i] * sb); T1[pa * 72 + pb] = (bf16_t)f2bf(tr[i] * sbe); }
.Lfs_outsel:
	s_cmp_eq_u32 s1, 0
	s_cbranch_scc0 .Lfs_out1
	v_pk_mul_f32 v[114:115], v[2:3], v[56:57] op_sel_hi:[1,0]
	v_pk_mul_f32 v[118:119], v[2:3], v[60:61] op_sel_hi:[1,0]
	v_cvt_pk_bf16_f32 v174, v114, v115
	v_cvt_pk_bf16_f32 v175, v118, v119
	ds_write_b16 v64, v174
	ds_write_b16_d16_hi v64, v174 offset:144
	ds_write_b16 v64, v175 offset:9216
	ds_write_b16_d16_hi v64, v175 offset:9360
	v_pk_mul_f32 v[114:115], v[4:5], v[56:57] op_sel_hi:[1,0]
	v_pk_mul_f32 v[118:119], v[4:5], v[60:61] op_sel_hi:[1,0]
	v_cvt_pk_bf16_f32 v174, v114, v115
	v_cvt_pk_bf16_f32 v175, v118, v119
	ds_write_b16 v64, v174 offset:1152
	ds_write_b16_d16_hi v64, v174 offset:1296
	ds_write_b16 v64, v175 offset:10368
	ds_write_b16_d16_hi v64, v175 offset:10512
	v_pk_mul_f32 v[114:115], v[8:9], v[56:57] op_sel_hi:[1,0]
	v_pk_mul_f32 v[118:119], v[8:9], v[60:61] op_sel_hi:[1,0]
	v_cvt_pk_bf16_f32 v174, v114, v115
	v_cvt_pk_bf16_f32 v175, v118, v119
	ds_write_b16 v64, v174 offset:2304
	ds_write_b16_d16_hi v64, v174 offset:2448
	ds_write_b16 v64, v175 offset:11520
	ds_write_b16_d16_hi v64, v175 offset:11664
	v_pk_mul_f32 v[114:115], v[10:11], v[56:57] op_sel_hi:[1,0]
	v_pk_mul_f32 v[118:119], v[10:11], v[60:61] op_sel_hi:[1,0]
	v_cvt_pk_bf16_f32 v174, v114, v115
	v_cvt_pk_bf16_f32 v175, v118, v119
	ds_write_b16 v64, v174 offset:3456
	ds_write_b16_d16_hi v64, v174 offset:3600
	ds_write_b16 v64, v175 offset:12672
	ds_write_b16_d16_hi v64, v175 offset:12816
	v_pk_mul_f32 v[114:115], v[18:19], v[56:57] op_sel_hi:[1,0]
	v_pk_mul_f32 v[118:119], v[18:19], v[60:61] op_sel_hi:[1,0]
	v_cvt_pk_bf16_f32 v174, v114, v115
	v_cvt_pk_bf16_f32 v175, v118, v119
	ds_write_b16 v64, v174 offset:4608
	ds_write_b16_d16_hi v64, v174 offset:4752
	ds_write_b16 v64, v175 offset:13824
	ds_write_b16_d16_hi v64, v175 offset:13968
	v_pk_mul_f32 v[114:115], v[50:51], v[56:57] op_sel_hi:[1,0]
	v_pk_mul_f32 v[118:119], v[50:51], v[60:61] op_sel_hi:[1,0]
	v_cvt_pk_bf16_f32 v174, v114, v115
	v_cvt_pk_bf16_f32 v175, v118, v119
	ds_write_b16 v64, v174 offset:5760
	ds_write_b16_d16_hi v64, v174 offset:5904
	ds_write_b16 v64, v175 offset:14976
	ds_write_b16_d16_hi v64, v175 offset:15120
	v_pk_mul_f32 v[114:115], v[54:55], v[56:57] op_sel_hi:[1,0]
	v_pk_mul_f32 v[118:119], v[54:55], v[60:61] op_sel_hi:[1,0]
	v_cvt_pk_bf16_f32 v174, v114, v115
	v_cvt_pk_bf16_f32 v175, v118, v119
	ds_write_b16 v64, v174 offset:6912
	ds_write_b16_d16_hi v64, v174 offset:7056
	ds_write_b16 v64, v175 offset:16128
	ds_write_b16_d16_hi v64, v175 offset:16272
	v_pk_mul_f32 v[114:115], v[58:59], v[56:57] op_sel_hi:[1,0]
	v_pk_mul_f32 v[118:119], v[58:59], v[60:61] op_sel_hi:[1,0]
	v_cvt_pk_bf16_f32 v174, v114, v115
	v_cvt_pk_bf16_f32 v175, v118, v119
	ds_write_b16 v64, v174 offset:8064
	ds_write_b16_d16_hi v64, v174 offset:8208
	ds_write_b16 v64, v175 offset:17280
	ds_write_b16_d16_hi v64, v175 offset:17424
	s_branch .Lfs_done
